# MFMA-wave stream cleanup: dead RSS branch removed from the non-peeled int8/w_in/w_out loops, mid s_setprio pairs removed from half-mode loops
# speedup vs baseline: 1.0027x; 1.0027x over previous
.LBB0_293:
	v_add_u32_e32 v132, 0, v243
	v_add_u32_e32 v133, 0x10000, v132
	v_add_u32_e32 v144, 0x14000, v132
	ds_read_b128 v[148:151], v133
	ds_read_b128 v[152:155], v133 offset:1024
	ds_read_b128 v[156:159], v133 offset:2048
	ds_read_b128 v[160:163], v133 offset:3072
	ds_read_b128 v[132:135], v144
	ds_read_b128 v[136:139], v144 offset:1024
	ds_read_b128 v[140:143], v144 offset:2048
	ds_read_b128 v[144:147], v144 offset:3072
	v_lshl_add_u64 v[246:247], v[224:225], 0, s[34:35]
	s_add_i32 m0, s63, 0xc000
	ds_read_b128 v[188:191], v244
	ds_read_b128 v[192:195], v244 offset:1024
	ds_read_b128 v[180:183], v244 offset:2048
	ds_read_b128 v[184:187], v244 offset:3072
	ds_read_b128 v[172:175], v244 offset:4096
	ds_read_b128 v[176:179], v244 offset:5120
	ds_read_b128 v[164:167], v244 offset:6144
	ds_read_b128 v[168:171], v244 offset:7168
	global_load_lds_dwordx4 v[246:247], off
	v_lshl_add_u64 v[246:247], v[226:227], 0, s[34:35]
	s_add_i32 m0, s63, 0xe000
	s_cmp_eq_u32 s34, 0
	global_load_lds_dwordx4 v[246:247], off
	s_waitcnt vmcnt(8)
	s_waitcnt lgkmcnt(0)
	s_cselect_b64 s[36:37], -1, 0
	s_and_b64 s[36:37], s[36:37], s[12:13]
	s_andn2_b64 vcc, exec, s[36:37]
	s_add_u32 s36, s28, s34
	s_addc_u32 s37, s29, s35
	s_add_u32 s36, s36, 0x100
	s_addc_u32 s37, s37, 0
	s_add_u32 s77, s27, s34
	s_addc_u32 s78, s31, s35
	s_cmpk_eq_i32 s34, 0x700
	s_cselect_b32 s43, s21, s37
	s_cselect_b32 s42, s74, s36
	s_cselect_b32 s37, s17, s78
	s_cselect_b32 s36, s75, s77
	s_setprio 1
	s_barrier
.LBB0_292:
	v_mfma_i32_16x16x64_i8 v[128:131], v[148:151], v[188:191], v[128:131]
	v_mfma_i32_16x16x64_i8 v[128:131], v[152:155], v[192:195], v[128:131]
	v_mfma_i32_16x16x64_i8 v[120:123], v[156:159], v[188:191], v[120:123]
	v_mfma_i32_16x16x64_i8 v[120:123], v[160:163], v[192:195], v[120:123]
	v_mfma_i32_16x16x64_i8 v[112:115], v[148:151], v[180:183], v[112:115]
	v_mfma_i32_16x16x64_i8 v[112:115], v[152:155], v[184:187], v[112:115]
	v_mfma_i32_16x16x64_i8 v[104:107], v[156:159], v[180:183], v[104:107]
	v_mfma_i32_16x16x64_i8 v[104:107], v[160:163], v[184:187], v[104:107]
	v_mfma_i32_16x16x64_i8 v[96:99], v[148:151], v[172:175], v[96:99]
	v_mfma_i32_16x16x64_i8 v[96:99], v[152:155], v[176:179], v[96:99]
	v_mfma_i32_16x16x64_i8 v[88:91], v[156:159], v[172:175], v[88:91]
	v_mfma_i32_16x16x64_i8 v[88:91], v[160:163], v[176:179], v[88:91]
	v_mfma_i32_16x16x64_i8 v[80:83], v[148:151], v[164:167], v[80:83]
	v_mfma_i32_16x16x64_i8 v[80:83], v[152:155], v[168:171], v[80:83]
	v_mfma_i32_16x16x64_i8 v[72:75], v[156:159], v[164:167], v[72:75]
	v_mfma_i32_16x16x64_i8 v[72:75], v[160:163], v[168:171], v[72:75]
	v_mfma_i32_16x16x64_i8 v[124:127], v[132:135], v[188:191], v[124:127]
	v_mfma_i32_16x16x64_i8 v[124:127], v[136:139], v[192:195], v[124:127]
	v_mfma_i32_16x16x64_i8 v[116:119], v[140:143], v[188:191], v[116:119]
	v_mfma_i32_16x16x64_i8 v[116:119], v[144:147], v[192:195], v[116:119]
	v_mfma_i32_16x16x64_i8 v[108:111], v[132:135], v[180:183], v[108:111]
	v_mfma_i32_16x16x64_i8 v[108:111], v[136:139], v[184:187], v[108:111]
	v_mfma_i32_16x16x64_i8 v[100:103], v[140:143], v[180:183], v[100:103]
	v_mfma_i32_16x16x64_i8 v[100:103], v[144:147], v[184:187], v[100:103]
	v_mfma_i32_16x16x64_i8 v[92:95], v[132:135], v[172:175], v[92:95]
	v_mfma_i32_16x16x64_i8 v[92:95], v[136:139], v[176:179], v[92:95]
	v_mfma_i32_16x16x64_i8 v[84:87], v[140:143], v[172:175], v[84:87]
	v_mfma_i32_16x16x64_i8 v[84:87], v[144:147], v[176:179], v[84:87]
	v_mfma_i32_16x16x64_i8 v[76:79], v[132:135], v[164:167], v[76:79]
	v_mfma_i32_16x16x64_i8 v[76:79], v[136:139], v[168:171], v[76:79]
	v_mfma_i32_16x16x64_i8 v[68:71], v[140:143], v[164:167], v[68:71]
	v_mfma_i32_16x16x64_i8 v[68:71], v[144:147], v[168:171], v[68:71]
	s_barrier
	s_setprio 0
	s_mov_b32 m0, s64
	v_lshl_add_u64 v[246:247], s[36:37], 0, v[34:35]
	s_add_u32 vcc_lo, s36, 0x40000
	ds_read_b128 v[164:167], v244 offset:16384
	ds_read_b128 v[168:171], v244 offset:17408
	ds_read_b128 v[172:175], v244 offset:18432
	ds_read_b128 v[176:179], v244 offset:19456
	ds_read_b128 v[180:183], v244 offset:20480
	ds_read_b128 v[184:187], v244 offset:21504
	ds_read_b128 v[188:191], v244 offset:22528
	ds_read_b128 v[192:195], v244 offset:23552
	global_load_lds_dwordx4 v[246:247], off
	v_lshl_add_u64 v[248:249], s[36:37], 0, v[210:211]
	s_mov_b32 m0, s65
	s_addc_u32 vcc_hi, s37, 0
	global_load_lds_dwordx4 v[248:249], off
	v_lshl_add_u64 v[250:251], vcc, 0, v[34:35]
	s_mov_b32 m0, s66
	v_lshl_add_u64 v[198:199], s[42:43], 0, v[208:209]
	global_load_lds_dwordx4 v[250:251], off
	v_lshl_add_u64 v[250:251], vcc, 0, v[210:211]
	s_mov_b32 m0, s67
	s_nop 0
	global_load_lds_dwordx4 v[250:251], off
	v_lshl_add_u64 v[250:251], s[42:43], 0, v[206:207]
	s_mov_b32 m0, s63
	s_nop 0
	global_load_lds_dwordx4 v[250:251], off
	s_mov_b32 m0, s68
	s_nop 0
	global_load_lds_dwordx4 v[198:199], off
	s_waitcnt vmcnt(8)
	s_waitcnt lgkmcnt(0)
	s_setprio 1
	s_barrier
	v_mfma_i32_16x16x64_i8 v[64:67], v[148:151], v[164:167], v[64:67]
	v_mfma_i32_16x16x64_i8 v[64:67], v[152:155], v[168:171], v[64:67]
	v_mfma_i32_16x16x64_i8 v[56:59], v[156:159], v[164:167], v[56:59]
	v_mfma_i32_16x16x64_i8 v[56:59], v[160:163], v[168:171], v[56:59]
	v_mfma_i32_16x16x64_i8 v[48:51], v[148:151], v[172:175], v[48:51]
	v_mfma_i32_16x16x64_i8 v[48:51], v[152:155], v[176:179], v[48:51]
	v_mfma_i32_16x16x64_i8 v[40:43], v[156:159], v[172:175], v[40:43]
	v_mfma_i32_16x16x64_i8 v[40:43], v[160:163], v[176:179], v[40:43]
	v_mfma_i32_16x16x64_i8 v[30:33], v[148:151], v[180:183], v[30:33]
	v_mfma_i32_16x16x64_i8 v[30:33], v[152:155], v[184:187], v[30:33]
	v_mfma_i32_16x16x64_i8 v[22:25], v[156:159], v[180:183], v[22:25]
	v_mfma_i32_16x16x64_i8 v[22:25], v[160:163], v[184:187], v[22:25]
	v_mfma_i32_16x16x64_i8 v[14:17], v[148:151], v[188:191], v[14:17]
	v_mfma_i32_16x16x64_i8 v[14:17], v[152:155], v[192:195], v[14:17]
	v_mfma_i32_16x16x64_i8 v[6:9], v[156:159], v[188:191], v[6:9]
	v_mfma_i32_16x16x64_i8 v[6:9], v[160:163], v[192:195], v[6:9]
	v_mfma_i32_16x16x64_i8 v[60:63], v[132:135], v[164:167], v[60:63]
	v_mfma_i32_16x16x64_i8 v[60:63], v[136:139], v[168:171], v[60:63]
	v_mfma_i32_16x16x64_i8 v[52:55], v[140:143], v[164:167], v[52:55]
	v_mfma_i32_16x16x64_i8 v[52:55], v[144:147], v[168:171], v[52:55]
	v_mfma_i32_16x16x64_i8 v[44:47], v[132:135], v[172:175], v[44:47]
	v_mfma_i32_16x16x64_i8 v[44:47], v[136:139], v[176:179], v[44:47]
	v_mfma_i32_16x16x64_i8 v[36:39], v[140:143], v[172:175], v[36:39]
	v_mfma_i32_16x16x64_i8 v[36:39], v[144:147], v[176:179], v[36:39]
	v_mfma_i32_16x16x64_i8 v[26:29], v[132:135], v[180:183], v[26:29]
	v_mfma_i32_16x16x64_i8 v[26:29], v[136:139], v[184:187], v[26:29]
	v_mfma_i32_16x16x64_i8 v[18:21], v[140:143], v[180:183], v[18:21]
	v_mfma_i32_16x16x64_i8 v[18:21], v[144:147], v[184:187], v[18:21]
	v_mfma_i32_16x16x64_i8 v[10:13], v[132:135], v[188:191], v[10:13]
	v_mfma_i32_16x16x64_i8 v[10:13], v[136:139], v[192:195], v[10:13]
	v_mfma_i32_16x16x64_i8 v[2:5], v[140:143], v[188:191], v[2:5]
	v_mfma_i32_16x16x64_i8 v[2:5], v[144:147], v[192:195], v[2:5]
	s_barrier
	s_setprio 0
	s_add_i32 s77, 0, 0x18000
	s_add_i32 s78, 0, 0x1c000
	v_add_u32_e32 v144, s77, v243
	v_add_u32_e32 v160, s78, v243
	ds_read_b128 v[132:135], v144
	ds_read_b128 v[136:139], v144 offset:1024
	ds_read_b128 v[140:143], v144 offset:2048
	ds_read_b128 v[144:147], v144 offset:3072
	ds_read_b128 v[148:151], v160
	ds_read_b128 v[152:155], v160 offset:1024
	ds_read_b128 v[156:159], v160 offset:2048
	ds_read_b128 v[160:163], v160 offset:3072
	s_add_u32 s42, s42, 0x40000
	s_addc_u32 s43, s43, 0
	s_mov_b32 m0, s69
	v_lshl_add_u64 v[200:201], s[42:43], 0, v[206:207]
	ds_read_b128 v[164:167], v244 offset:32768
	ds_read_b128 v[168:171], v244 offset:33792
	ds_read_b128 v[172:175], v244 offset:34816
	ds_read_b128 v[176:179], v244 offset:35840
	ds_read_b128 v[180:183], v244 offset:36864
	ds_read_b128 v[184:187], v244 offset:37888
	ds_read_b128 v[188:191], v244 offset:38912
	ds_read_b128 v[192:195], v244 offset:39936
	global_load_lds_dwordx4 v[200:201], off
	v_lshl_add_u64 v[200:201], s[42:43], 0, v[208:209]
	s_mov_b32 m0, s70
	s_nop 0
	global_load_lds_dwordx4 v[200:201], off
	s_waitcnt vmcnt(8)
	s_waitcnt lgkmcnt(0)
	s_setprio 1
	s_barrier
	v_mfma_i32_16x16x64_i8 v[128:131], v[132:135], v[164:167], v[128:131]
	v_mfma_i32_16x16x64_i8 v[128:131], v[136:139], v[168:171], v[128:131]
	v_mfma_i32_16x16x64_i8 v[120:123], v[140:143], v[164:167], v[120:123]
	v_mfma_i32_16x16x64_i8 v[120:123], v[144:147], v[168:171], v[120:123]
	v_mfma_i32_16x16x64_i8 v[112:115], v[132:135], v[172:175], v[112:115]
	v_mfma_i32_16x16x64_i8 v[112:115], v[136:139], v[176:179], v[112:115]
	v_mfma_i32_16x16x64_i8 v[104:107], v[140:143], v[172:175], v[104:107]
	v_mfma_i32_16x16x64_i8 v[104:107], v[144:147], v[176:179], v[104:107]
	v_mfma_i32_16x16x64_i8 v[96:99], v[132:135], v[180:183], v[96:99]
	v_mfma_i32_16x16x64_i8 v[96:99], v[136:139], v[184:187], v[96:99]
	v_mfma_i32_16x16x64_i8 v[88:91], v[140:143], v[180:183], v[88:91]
	v_mfma_i32_16x16x64_i8 v[88:91], v[144:147], v[184:187], v[88:91]
	v_mfma_i32_16x16x64_i8 v[80:83], v[132:135], v[188:191], v[80:83]
	v_mfma_i32_16x16x64_i8 v[80:83], v[136:139], v[192:195], v[80:83]
	v_mfma_i32_16x16x64_i8 v[72:75], v[140:143], v[188:191], v[72:75]
	v_mfma_i32_16x16x64_i8 v[72:75], v[144:147], v[192:195], v[72:75]
	v_mfma_i32_16x16x64_i8 v[124:127], v[148:151], v[164:167], v[124:127]
	v_mfma_i32_16x16x64_i8 v[124:127], v[152:155], v[168:171], v[124:127]
	v_mfma_i32_16x16x64_i8 v[116:119], v[156:159], v[164:167], v[116:119]
	v_mfma_i32_16x16x64_i8 v[116:119], v[160:163], v[168:171], v[116:119]
	v_mfma_i32_16x16x64_i8 v[108:111], v[148:151], v[172:175], v[108:111]
	v_mfma_i32_16x16x64_i8 v[108:111], v[152:155], v[176:179], v[108:111]
	v_mfma_i32_16x16x64_i8 v[100:103], v[156:159], v[172:175], v[100:103]
	v_mfma_i32_16x16x64_i8 v[100:103], v[160:163], v[176:179], v[100:103]
	v_mfma_i32_16x16x64_i8 v[92:95], v[148:151], v[180:183], v[92:95]
	v_mfma_i32_16x16x64_i8 v[92:95], v[152:155], v[184:187], v[92:95]
	v_mfma_i32_16x16x64_i8 v[84:87], v[156:159], v[180:183], v[84:87]
	v_mfma_i32_16x16x64_i8 v[84:87], v[160:163], v[184:187], v[84:87]
	v_mfma_i32_16x16x64_i8 v[76:79], v[148:151], v[188:191], v[76:79]
	v_mfma_i32_16x16x64_i8 v[76:79], v[152:155], v[192:195], v[76:79]
	v_mfma_i32_16x16x64_i8 v[68:71], v[156:159], v[188:191], v[68:71]
	v_mfma_i32_16x16x64_i8 v[68:71], v[160:163], v[192:195], v[68:71]
	s_barrier
	s_setprio 0
	s_add_i32 s42, s77, s62
	v_lshl_add_u64 v[200:201], v[246:247], 0, s[18:19]
	s_mov_b32 m0, s42
	ds_read_b128 v[164:167], v244 offset:49152
	ds_read_b128 v[168:171], v244 offset:50176
	ds_read_b128 v[172:175], v244 offset:51200
	ds_read_b128 v[176:179], v244 offset:52224
	ds_read_b128 v[180:183], v244 offset:53248
	ds_read_b128 v[184:187], v244 offset:54272
	ds_read_b128 v[188:191], v244 offset:55296
	ds_read_b128 v[192:195], v244 offset:56320
	global_load_lds_dwordx4 v[200:201], off
	s_add_i32 m0, s42, 0x2000
	s_add_u32 s36, s36, 0x40080
	v_lshl_add_u64 v[200:201], v[248:249], 0, s[18:19]
	s_addc_u32 s37, s37, 0
	s_add_i32 s42, s78, s62
	global_load_lds_dwordx4 v[200:201], off
	v_lshl_add_u64 v[200:201], s[36:37], 0, v[34:35]
	s_mov_b32 m0, s42
	v_lshl_add_u64 v[198:199], v[198:199], 0, s[18:19]
	global_load_lds_dwordx4 v[200:201], off
	v_lshl_add_u64 v[200:201], s[36:37], 0, v[210:211]
	s_add_i32 m0, s42, 0x2000
	s_nop 0
	global_load_lds_dwordx4 v[200:201], off
	v_lshl_add_u64 v[200:201], v[250:251], 0, s[18:19]
	s_mov_b32 m0, s71
	s_nop 0
	global_load_lds_dwordx4 v[200:201], off
	s_mov_b32 m0, s72
	s_nop 0
	global_load_lds_dwordx4 v[198:199], off
	s_waitcnt vmcnt(8)
	s_waitcnt lgkmcnt(0)
	s_setprio 1
	s_barrier
	v_mfma_i32_16x16x64_i8 v[64:67], v[132:135], v[164:167], v[64:67]
	v_mfma_i32_16x16x64_i8 v[64:67], v[136:139], v[168:171], v[64:67]
	v_mfma_i32_16x16x64_i8 v[56:59], v[140:143], v[164:167], v[56:59]
	v_mfma_i32_16x16x64_i8 v[56:59], v[144:147], v[168:171], v[56:59]
	v_mfma_i32_16x16x64_i8 v[48:51], v[132:135], v[172:175], v[48:51]
	v_mfma_i32_16x16x64_i8 v[48:51], v[136:139], v[176:179], v[48:51]
	v_mfma_i32_16x16x64_i8 v[40:43], v[140:143], v[172:175], v[40:43]
	v_mfma_i32_16x16x64_i8 v[40:43], v[144:147], v[176:179], v[40:43]
	v_mfma_i32_16x16x64_i8 v[30:33], v[132:135], v[180:183], v[30:33]
	v_mfma_i32_16x16x64_i8 v[30:33], v[136:139], v[184:187], v[30:33]
	v_mfma_i32_16x16x64_i8 v[22:25], v[140:143], v[180:183], v[22:25]
	v_mfma_i32_16x16x64_i8 v[22:25], v[144:147], v[184:187], v[22:25]
	v_mfma_i32_16x16x64_i8 v[14:17], v[132:135], v[188:191], v[14:17]
	v_mfma_i32_16x16x64_i8 v[14:17], v[136:139], v[192:195], v[14:17]
	v_mfma_i32_16x16x64_i8 v[6:9], v[140:143], v[188:191], v[6:9]
	v_mfma_i32_16x16x64_i8 v[6:9], v[144:147], v[192:195], v[6:9]
	v_mfma_i32_16x16x64_i8 v[60:63], v[148:151], v[164:167], v[60:63]
	v_mfma_i32_16x16x64_i8 v[60:63], v[152:155], v[168:171], v[60:63]
	v_mfma_i32_16x16x64_i8 v[52:55], v[156:159], v[164:167], v[52:55]
	v_mfma_i32_16x16x64_i8 v[52:55], v[160:163], v[168:171], v[52:55]
	v_mfma_i32_16x16x64_i8 v[44:47], v[148:151], v[172:175], v[44:47]
	v_mfma_i32_16x16x64_i8 v[44:47], v[152:155], v[176:179], v[44:47]
	v_mfma_i32_16x16x64_i8 v[36:39], v[156:159], v[172:175], v[36:39]
	v_mfma_i32_16x16x64_i8 v[36:39], v[160:163], v[176:179], v[36:39]
	v_mfma_i32_16x16x64_i8 v[26:29], v[148:151], v[180:183], v[26:29]
	v_mfma_i32_16x16x64_i8 v[26:29], v[152:155], v[184:187], v[26:29]
	v_mfma_i32_16x16x64_i8 v[18:21], v[156:159], v[180:183], v[18:21]
	v_mfma_i32_16x16x64_i8 v[18:21], v[160:163], v[184:187], v[18:21]
	v_mfma_i32_16x16x64_i8 v[10:13], v[148:151], v[188:191], v[10:13]
	v_mfma_i32_16x16x64_i8 v[10:13], v[152:155], v[192:195], v[10:13]
	v_mfma_i32_16x16x64_i8 v[2:5], v[156:159], v[188:191], v[2:5]
	v_mfma_i32_16x16x64_i8 v[2:5], v[160:163], v[192:195], v[2:5]
	s_barrier
	s_setprio 0
	s_add_i32 s76, s76, 2
	s_add_u32 s34, s34, 0x100
	s_addc_u32 s35, s35, 0
	s_cmp_gt_u32 s76, 13
	s_cbranch_scc0 .LBB0_293
	s_branch .LBB0_295

.LBB0_344:
	s_cmp_eq_u32 s45, 12
	s_cselect_b32 s73, s21, s29
	s_cselect_b32 s72, s43, s27
	s_cselect_b32 s35, s17, s37
	s_cselect_b32 s34, s44, s36
	s_setprio 1
	s_waitcnt lgkmcnt(0)
	v_mfma_i32_16x16x64_i8 v[64:67], v[100:103], v[124:127], v[64:67]
	v_mfma_i32_16x16x64_i8 v[56:59], v[108:111], v[124:127], v[56:59]
	v_mfma_i32_16x16x64_i8 v[48:51], v[100:103], v[116:119], v[48:51]
	v_mfma_i32_16x16x64_i8 v[40:43], v[108:111], v[116:119], v[40:43]
	v_mfma_i32_16x16x64_i8 v[30:33], v[100:103], v[92:95], v[30:33]
	v_mfma_i32_16x16x64_i8 v[22:25], v[108:111], v[92:95], v[22:25]
	v_mfma_i32_16x16x64_i8 v[14:17], v[100:103], v[84:87], v[14:17]
	v_mfma_i32_16x16x64_i8 v[6:9], v[108:111], v[84:87], v[6:9]
	v_mfma_i32_16x16x64_i8 v[64:67], v[104:107], v[128:131], v[64:67]
	v_mfma_i32_16x16x64_i8 v[56:59], v[112:115], v[128:131], v[56:59]
	v_mfma_i32_16x16x64_i8 v[48:51], v[104:107], v[120:123], v[48:51]
	v_mfma_i32_16x16x64_i8 v[40:43], v[112:115], v[120:123], v[40:43]
	v_mfma_i32_16x16x64_i8 v[30:33], v[104:107], v[96:99], v[30:33]
	v_mfma_i32_16x16x64_i8 v[22:25], v[112:115], v[96:99], v[22:25]
	v_mfma_i32_16x16x64_i8 v[14:17], v[104:107], v[88:91], v[14:17]
	v_mfma_i32_16x16x64_i8 v[6:9], v[112:115], v[88:91], v[6:9]
	v_mfma_i32_16x16x64_i8 v[60:63], v[68:71], v[124:127], v[60:63]
	v_mfma_i32_16x16x64_i8 v[52:55], v[76:79], v[124:127], v[52:55]
	v_mfma_i32_16x16x64_i8 v[44:47], v[68:71], v[116:119], v[44:47]
	v_mfma_i32_16x16x64_i8 v[36:39], v[76:79], v[116:119], v[36:39]
	v_mfma_i32_16x16x64_i8 v[26:29], v[68:71], v[92:95], v[26:29]
	v_mfma_i32_16x16x64_i8 v[18:21], v[76:79], v[92:95], v[18:21]
	v_mfma_i32_16x16x64_i8 v[10:13], v[68:71], v[84:87], v[10:13]
	v_mfma_i32_16x16x64_i8 v[2:5], v[76:79], v[84:87], v[2:5]
	v_mfma_i32_16x16x64_i8 v[60:63], v[72:75], v[128:131], v[60:63]
	v_mfma_i32_16x16x64_i8 v[52:55], v[80:83], v[128:131], v[52:55]
	v_mfma_i32_16x16x64_i8 v[44:47], v[72:75], v[120:123], v[44:47]
	v_mfma_i32_16x16x64_i8 v[36:39], v[80:83], v[120:123], v[36:39]
	v_mfma_i32_16x16x64_i8 v[26:29], v[72:75], v[96:99], v[26:29]
	v_mfma_i32_16x16x64_i8 v[18:21], v[80:83], v[96:99], v[18:21]
	v_mfma_i32_16x16x64_i8 v[10:13], v[72:75], v[88:91], v[10:13]
	v_mfma_i32_16x16x64_i8 v[2:5], v[80:83], v[88:91], v[2:5]
	s_setprio 0
	s_barrier
	s_mov_b32 m0, s64
	v_lshl_add_u64 v[142:143], s[34:35], 0, v[34:35]
	s_add_u32 s74, s34, 0x40000
	global_load_lds_dwordx4 v[142:143], off
	v_lshl_add_u64 v[144:145], s[34:35], 0, v[210:211]
	s_mov_b32 m0, s65
	s_addc_u32 s75, s35, 0
	global_load_lds_dwordx4 v[144:145], off
	v_lshl_add_u64 v[68:69], s[74:75], 0, v[34:35]
	s_mov_b32 m0, s66
	v_lshl_add_u64 v[146:147], s[72:73], 0, v[206:207]
	global_load_lds_dwordx4 v[68:69], off
	v_lshl_add_u64 v[68:69], s[74:75], 0, v[210:211]
	s_mov_b32 m0, s67
	v_lshl_add_u64 v[148:149], s[72:73], 0, v[208:209]
	global_load_lds_dwordx4 v[68:69], off
	s_mov_b32 m0, s63
	s_nop 0
	global_load_lds_dwordx4 v[146:147], off
	s_mov_b32 m0, s68
	s_nop 0
	global_load_lds_dwordx4 v[148:149], off
	s_waitcnt vmcnt(6)
	s_barrier
	s_barrier
	s_add_i32 s71, 0, 0x18000
	s_add_i32 s72, 0, 0x1c000
	v_add_u32_e32 v80, s71, v140
	v_add_u32_e32 v96, s72, v140
	ds_read_b128 v[68:71], v80
	ds_read_b128 v[72:75], v80 offset:1024
	ds_read_b128 v[76:79], v80 offset:2048
	ds_read_b128 v[80:83], v80 offset:3072
	ds_read_b128 v[84:87], v96
	ds_read_b128 v[88:91], v96 offset:1024
	ds_read_b128 v[92:95], v96 offset:2048
	ds_read_b128 v[96:99], v96 offset:3072
	ds_read_b128 v[100:103], v141 offset:32768
	ds_read_b128 v[104:107], v141 offset:33792
	ds_read_b128 v[108:111], v141 offset:34816
	ds_read_b128 v[112:115], v141 offset:35840
	ds_read_b128 v[116:119], v141 offset:36864
	ds_read_b128 v[120:123], v141 offset:37888
	ds_read_b128 v[124:127], v141 offset:38912
	ds_read_b128 v[128:131], v141 offset:39936
	s_waitcnt lgkmcnt(0)
	s_barrier
	s_setprio 1
	s_waitcnt lgkmcnt(0)
	v_mfma_i32_16x16x64_i8 v[64:67], v[68:71], v[100:103], v[64:67]
	v_mfma_i32_16x16x64_i8 v[56:59], v[76:79], v[100:103], v[56:59]
	v_mfma_i32_16x16x64_i8 v[48:51], v[68:71], v[108:111], v[48:51]
	v_mfma_i32_16x16x64_i8 v[40:43], v[76:79], v[108:111], v[40:43]
	v_mfma_i32_16x16x64_i8 v[30:33], v[68:71], v[116:119], v[30:33]
	v_mfma_i32_16x16x64_i8 v[22:25], v[76:79], v[116:119], v[22:25]
	v_mfma_i32_16x16x64_i8 v[14:17], v[68:71], v[124:127], v[14:17]
	v_mfma_i32_16x16x64_i8 v[6:9], v[76:79], v[124:127], v[6:9]
	v_mfma_i32_16x16x64_i8 v[64:67], v[72:75], v[104:107], v[64:67]
	v_mfma_i32_16x16x64_i8 v[56:59], v[80:83], v[104:107], v[56:59]
	v_mfma_i32_16x16x64_i8 v[48:51], v[72:75], v[112:115], v[48:51]
	v_mfma_i32_16x16x64_i8 v[40:43], v[80:83], v[112:115], v[40:43]
	v_mfma_i32_16x16x64_i8 v[30:33], v[72:75], v[120:123], v[30:33]
	v_mfma_i32_16x16x64_i8 v[22:25], v[80:83], v[120:123], v[22:25]
	v_mfma_i32_16x16x64_i8 v[14:17], v[72:75], v[128:131], v[14:17]
	v_mfma_i32_16x16x64_i8 v[6:9], v[80:83], v[128:131], v[6:9]
	v_mfma_i32_16x16x64_i8 v[60:63], v[84:87], v[100:103], v[60:63]
	v_mfma_i32_16x16x64_i8 v[52:55], v[92:95], v[100:103], v[52:55]
	v_mfma_i32_16x16x64_i8 v[44:47], v[84:87], v[108:111], v[44:47]
	v_mfma_i32_16x16x64_i8 v[36:39], v[92:95], v[108:111], v[36:39]
	v_mfma_i32_16x16x64_i8 v[26:29], v[84:87], v[116:119], v[26:29]
	v_mfma_i32_16x16x64_i8 v[18:21], v[92:95], v[116:119], v[18:21]
	v_mfma_i32_16x16x64_i8 v[10:13], v[84:87], v[124:127], v[10:13]
	v_mfma_i32_16x16x64_i8 v[2:5], v[92:95], v[124:127], v[2:5]
	v_mfma_i32_16x16x64_i8 v[60:63], v[88:91], v[104:107], v[60:63]
	v_mfma_i32_16x16x64_i8 v[52:55], v[96:99], v[104:107], v[52:55]
	v_mfma_i32_16x16x64_i8 v[44:47], v[88:91], v[112:115], v[44:47]
	v_mfma_i32_16x16x64_i8 v[36:39], v[96:99], v[112:115], v[36:39]
	v_mfma_i32_16x16x64_i8 v[26:29], v[88:91], v[120:123], v[26:29]
	v_mfma_i32_16x16x64_i8 v[18:21], v[96:99], v[120:123], v[18:21]
	v_mfma_i32_16x16x64_i8 v[10:13], v[88:91], v[128:131], v[10:13]
	v_mfma_i32_16x16x64_i8 v[2:5], v[96:99], v[128:131], v[2:5]
	s_setprio 0
	s_barrier
	s_add_i32 s71, s71, s62
	v_lshl_add_u64 v[68:69], v[142:143], 0, s[18:19]
	s_mov_b32 m0, s71
	s_nop 0
	global_load_lds_dwordx4 v[68:69], off
	s_add_i32 m0, s71, 0x2000
	s_add_u32 s34, s34, 0x40080
	v_lshl_add_u64 v[68:69], v[144:145], 0, s[18:19]
	s_addc_u32 s35, s35, 0
	s_add_i32 s71, s72, s62
	global_load_lds_dwordx4 v[68:69], off
	v_lshl_add_u64 v[68:69], s[34:35], 0, v[34:35]
	s_mov_b32 m0, s71
	s_nop 0
	global_load_lds_dwordx4 v[68:69], off
	v_lshl_add_u64 v[68:69], s[34:35], 0, v[210:211]
	s_add_i32 m0, s71, 0x2000
	s_nop 0
	global_load_lds_dwordx4 v[68:69], off
	v_lshl_add_u64 v[68:69], v[146:147], 0, s[18:19]
	s_mov_b32 m0, s69
	s_nop 0
	global_load_lds_dwordx4 v[68:69], off
	v_lshl_add_u64 v[68:69], v[148:149], 0, s[18:19]
	s_mov_b32 m0, s70
	s_nop 0
	global_load_lds_dwordx4 v[68:69], off
	s_waitcnt vmcnt(6)
	s_barrier
	s_barrier
	s_add_i32 s45, s45, 2
	s_add_u32 s27, s27, 0x100
	s_addc_u32 s29, s29, 0
	s_add_u32 s36, s36, 0x100
	s_addc_u32 s37, s37, 0
	s_cmp_gt_u32 s45, 13
	s_cbranch_scc1 .LBB0_347

.LBB0_586:
	s_add_i32 s52, 0, 0x10000
	s_cmpk_eq_i32 s29, 0x54
	s_cselect_b32 s43, s21, s13
	s_cselect_b32 s42, s20, s11
	s_cselect_b32 s25, s23, s27
	s_cselect_b32 s24, s22, s26
	s_add_i32 s55, 0, 0x14000
	v_add_u32_e32 v72, s52, v110
	v_add_u32_e32 v96, s55, v110
	ds_read_b128 v[56:59], v72
	ds_read_b128 v[64:67], v72 offset:1024
	ds_read_b128 v[68:71], v72 offset:2048
	ds_read_b128 v[72:75], v72 offset:3072
	ds_read_b128 v[76:79], v96
	ds_read_b128 v[84:87], v96 offset:1024
	ds_read_b128 v[92:95], v96 offset:2048
	ds_read_b128 v[96:99], v96 offset:3072
	ds_read_b128 v[100:103], v111
	ds_read_b128 v[104:107], v111 offset:1024
	ds_read_b128 v[112:115], v111 offset:2048
	ds_read_b128 v[116:119], v111 offset:3072
	ds_read_b128 v[120:123], v111 offset:4096
	ds_read_b128 v[124:127], v111 offset:5120
	ds_read_b128 v[128:131], v111 offset:6144
	ds_read_b128 v[132:135], v111 offset:7168
	s_waitcnt lgkmcnt(0)
	s_barrier
	s_setprio 1
	s_waitcnt lgkmcnt(0)
	v_mfma_f32_16x16x32_bf16 v[88:91], v[56:59], v[100:103], v[88:91]
	v_mfma_f32_16x16x32_bf16 v[80:83], v[68:71], v[100:103], v[80:83]
	v_mfma_f32_16x16x32_bf16 v[48:51], v[56:59], v[112:115], v[48:51]
	v_mfma_f32_16x16x32_bf16 v[44:47], v[68:71], v[112:115], v[44:47]
	v_mfma_f32_16x16x32_bf16 v[30:33], v[56:59], v[120:123], v[30:33]
	v_mfma_f32_16x16x32_bf16 v[26:29], v[68:71], v[120:123], v[26:29]
	v_mfma_f32_16x16x32_bf16 v[14:17], v[56:59], v[128:131], v[14:17]
	v_mfma_f32_16x16x32_bf16 v[10:13], v[68:71], v[128:131], v[10:13]
	v_mfma_f32_16x16x32_bf16 v[88:91], v[64:67], v[104:107], v[88:91]
	v_mfma_f32_16x16x32_bf16 v[80:83], v[72:75], v[104:107], v[80:83]
	v_mfma_f32_16x16x32_bf16 v[48:51], v[64:67], v[116:119], v[48:51]
	v_mfma_f32_16x16x32_bf16 v[44:47], v[72:75], v[116:119], v[44:47]
	v_mfma_f32_16x16x32_bf16 v[30:33], v[64:67], v[124:127], v[30:33]
	v_mfma_f32_16x16x32_bf16 v[26:29], v[72:75], v[124:127], v[26:29]
	v_mfma_f32_16x16x32_bf16 v[14:17], v[64:67], v[132:135], v[14:17]
	v_mfma_f32_16x16x32_bf16 v[10:13], v[72:75], v[132:135], v[10:13]
	v_mfma_f32_16x16x32_bf16 v[52:55], v[92:95], v[100:103], v[52:55]
	v_mfma_f32_16x16x32_bf16 v[40:43], v[76:79], v[112:115], v[40:43]
	v_mfma_f32_16x16x32_bf16 v[36:39], v[92:95], v[112:115], v[36:39]
	v_mfma_f32_16x16x32_bf16 v[22:25], v[76:79], v[120:123], v[22:25]
	v_mfma_f32_16x16x32_bf16 v[18:21], v[92:95], v[120:123], v[18:21]
	v_mfma_f32_16x16x32_bf16 v[6:9], v[76:79], v[128:131], v[6:9]
	v_mfma_f32_16x16x32_bf16 v[2:5], v[92:95], v[128:131], v[2:5]
	v_mfma_f32_16x16x32_bf16 v[56:59], v[76:79], v[100:103], v[60:63]
	v_mfma_f32_16x16x32_bf16 v[52:55], v[96:99], v[104:107], v[52:55]
	v_mfma_f32_16x16x32_bf16 v[40:43], v[84:87], v[116:119], v[40:43]
	v_mfma_f32_16x16x32_bf16 v[36:39], v[96:99], v[116:119], v[36:39]
	v_mfma_f32_16x16x32_bf16 v[22:25], v[84:87], v[124:127], v[22:25]
	v_mfma_f32_16x16x32_bf16 v[18:21], v[96:99], v[124:127], v[18:21]
	v_mfma_f32_16x16x32_bf16 v[6:9], v[84:87], v[132:135], v[6:9]
	v_mfma_f32_16x16x32_bf16 v[2:5], v[96:99], v[132:135], v[2:5]
	v_mfma_f32_16x16x32_bf16 v[56:59], v[84:87], v[104:107], v[56:59]
	s_setprio 0
	s_barrier
	s_add_i32 s52, s52, s30
	v_lshl_add_u64 v[108:109], s[24:25], 0, v[34:35]
	s_mov_b32 m0, s52
	v_lshl_add_u64 v[136:137], s[24:25], 0, v[164:165]
	global_load_lds_dwordx4 v[108:109], off
	s_add_i32 m0, s52, 0x2000
	s_add_u32 s60, s24, 0x160000
	s_addc_u32 s61, s25, 0
	s_add_i32 s52, s55, s30
	global_load_lds_dwordx4 v[136:137], off
	v_lshl_add_u64 v[60:61], s[60:61], 0, v[34:35]
	s_mov_b32 m0, s52
	v_lshl_add_u64 v[138:139], s[42:43], 0, v[160:161]
	global_load_lds_dwordx4 v[60:61], off
	v_lshl_add_u64 v[60:61], s[60:61], 0, v[164:165]
	s_add_i32 m0, s52, 0x2000
	v_lshl_add_u64 v[140:141], s[42:43], 0, v[162:163]
	global_load_lds_dwordx4 v[60:61], off
	s_mov_b32 m0, s31
	s_nop 0
	global_load_lds_dwordx4 v[138:139], off
	s_mov_b32 m0, s38
	s_nop 0
	global_load_lds_dwordx4 v[140:141], off
	s_waitcnt vmcnt(6)
	s_barrier
	s_barrier
	s_add_i32 s42, 0, 0x18000
	s_add_i32 s43, 0, 0x1c000
	v_add_u32_e32 v72, s42, v110
	v_add_u32_e32 v96, s43, v110
	ds_read_b128 v[60:63], v72
	ds_read_b128 v[64:67], v72 offset:1024
	ds_read_b128 v[68:71], v72 offset:2048
	ds_read_b128 v[72:75], v72 offset:3072
	ds_read_b128 v[76:79], v96
	ds_read_b128 v[84:87], v96 offset:1024
	ds_read_b128 v[92:95], v96 offset:2048
	ds_read_b128 v[96:99], v96 offset:3072
	ds_read_b128 v[100:103], v111 offset:32768
	ds_read_b128 v[104:107], v111 offset:33792
	ds_read_b128 v[112:115], v111 offset:34816
	ds_read_b128 v[116:119], v111 offset:35840
	ds_read_b128 v[120:123], v111 offset:36864
	ds_read_b128 v[124:127], v111 offset:37888
	ds_read_b128 v[128:131], v111 offset:38912
	ds_read_b128 v[132:135], v111 offset:39936
	s_waitcnt lgkmcnt(0)
	s_barrier
	s_setprio 1
	s_waitcnt lgkmcnt(0)
	v_mfma_f32_16x16x32_bf16 v[88:91], v[60:63], v[100:103], v[88:91]
	v_mfma_f32_16x16x32_bf16 v[80:83], v[68:71], v[100:103], v[80:83]
	v_mfma_f32_16x16x32_bf16 v[48:51], v[60:63], v[112:115], v[48:51]
	v_mfma_f32_16x16x32_bf16 v[44:47], v[68:71], v[112:115], v[44:47]
	v_mfma_f32_16x16x32_bf16 v[30:33], v[60:63], v[120:123], v[30:33]
	v_mfma_f32_16x16x32_bf16 v[26:29], v[68:71], v[120:123], v[26:29]
	v_mfma_f32_16x16x32_bf16 v[14:17], v[60:63], v[128:131], v[14:17]
	v_mfma_f32_16x16x32_bf16 v[10:13], v[68:71], v[128:131], v[10:13]
	v_mfma_f32_16x16x32_bf16 v[88:91], v[64:67], v[104:107], v[88:91]
	v_mfma_f32_16x16x32_bf16 v[80:83], v[72:75], v[104:107], v[80:83]
	v_mfma_f32_16x16x32_bf16 v[48:51], v[64:67], v[116:119], v[48:51]
	v_mfma_f32_16x16x32_bf16 v[44:47], v[72:75], v[116:119], v[44:47]
	v_mfma_f32_16x16x32_bf16 v[30:33], v[64:67], v[124:127], v[30:33]
	v_mfma_f32_16x16x32_bf16 v[26:29], v[72:75], v[124:127], v[26:29]
	v_mfma_f32_16x16x32_bf16 v[14:17], v[64:67], v[132:135], v[14:17]
	v_mfma_f32_16x16x32_bf16 v[10:13], v[72:75], v[132:135], v[10:13]
	v_mfma_f32_16x16x32_bf16 v[56:59], v[76:79], v[100:103], v[56:59]
	v_mfma_f32_16x16x32_bf16 v[52:55], v[92:95], v[100:103], v[52:55]
	v_mfma_f32_16x16x32_bf16 v[40:43], v[76:79], v[112:115], v[40:43]
	v_mfma_f32_16x16x32_bf16 v[36:39], v[92:95], v[112:115], v[36:39]
	v_mfma_f32_16x16x32_bf16 v[22:25], v[76:79], v[120:123], v[22:25]
	v_mfma_f32_16x16x32_bf16 v[18:21], v[92:95], v[120:123], v[18:21]
	v_mfma_f32_16x16x32_bf16 v[6:9], v[76:79], v[128:131], v[6:9]
	v_mfma_f32_16x16x32_bf16 v[2:5], v[92:95], v[128:131], v[2:5]
	v_mfma_f32_16x16x32_bf16 v[60:63], v[84:87], v[104:107], v[56:59]
	v_mfma_f32_16x16x32_bf16 v[52:55], v[96:99], v[104:107], v[52:55]
	v_mfma_f32_16x16x32_bf16 v[40:43], v[84:87], v[116:119], v[40:43]
	v_mfma_f32_16x16x32_bf16 v[36:39], v[96:99], v[116:119], v[36:39]
	v_mfma_f32_16x16x32_bf16 v[22:25], v[84:87], v[124:127], v[22:25]
	v_mfma_f32_16x16x32_bf16 v[18:21], v[96:99], v[124:127], v[18:21]
	v_mfma_f32_16x16x32_bf16 v[6:9], v[84:87], v[132:135], v[6:9]
	v_mfma_f32_16x16x32_bf16 v[2:5], v[96:99], v[132:135], v[2:5]
	s_setprio 0
	s_barrier
	s_add_i32 s42, s42, s30
	v_lshl_add_u64 v[56:57], v[108:109], 0, s[18:19]
	s_mov_b32 m0, s42
	s_nop 0
	global_load_lds_dwordx4 v[56:57], off
	s_add_i32 m0, s42, 0x2000
	s_add_u32 s24, s24, 0x160080
	v_lshl_add_u64 v[56:57], v[136:137], 0, s[18:19]
	s_addc_u32 s25, s25, 0
	s_add_i32 s42, s43, s30
	global_load_lds_dwordx4 v[56:57], off
	v_lshl_add_u64 v[56:57], s[24:25], 0, v[34:35]
	s_mov_b32 m0, s42
	s_nop 0
	global_load_lds_dwordx4 v[56:57], off
	v_lshl_add_u64 v[56:57], s[24:25], 0, v[164:165]
	s_add_i32 m0, s42, 0x2000
	s_nop 0
	global_load_lds_dwordx4 v[56:57], off
	v_lshl_add_u64 v[56:57], v[138:139], 0, s[18:19]
	s_mov_b32 m0, s39
	s_nop 0
	global_load_lds_dwordx4 v[56:57], off
	v_lshl_add_u64 v[56:57], v[140:141], 0, s[18:19]
	s_mov_b32 m0, s44
	s_nop 0
	global_load_lds_dwordx4 v[56:57], off
	s_waitcnt vmcnt(6)
	s_barrier
	s_barrier
	s_add_i32 s29, s29, 2
	s_add_u32 s11, s11, 0x100
	s_addc_u32 s13, s13, 0
	s_add_u32 s26, s26, 0x100
	s_addc_u32 s27, s27, 0
	s_cmpk_gt_u32 s29, 0x55
	s_cbranch_scc0 .LBB0_586
	s_and_b64 vcc, exec, s[16:17]
	s_cbranch_vccz .LBB0_589
	s_barrier

.LBB0_808:
	v_add_u32_e32 v34, 0, v227
	v_add_u32_e32 v132, 0x10000, v34
	v_add_u32_e32 v34, 0x14000, v34
	ds_read_b128 v[148:151], v132
	ds_read_b128 v[152:155], v132 offset:1024
	ds_read_b128 v[156:159], v132 offset:2048
	ds_read_b128 v[160:163], v132 offset:3072
	ds_read_b128 v[132:135], v34
	ds_read_b128 v[136:139], v34 offset:1024
	ds_read_b128 v[140:143], v34 offset:2048
	ds_read_b128 v[144:147], v34 offset:3072
	v_lshl_add_u64 v[198:199], v[222:223], 0, s[34:35]
	s_add_i32 m0, s47, 0xc000
	ds_read_b128 v[188:191], v240
	ds_read_b128 v[192:195], v240 offset:1024
	ds_read_b128 v[180:183], v240 offset:2048
	ds_read_b128 v[184:187], v240 offset:3072
	ds_read_b128 v[172:175], v240 offset:4096
	ds_read_b128 v[176:179], v240 offset:5120
	ds_read_b128 v[164:167], v240 offset:6144
	ds_read_b128 v[168:171], v240 offset:7168
	global_load_lds_dwordx4 v[198:199], off
	v_lshl_add_u64 v[198:199], v[224:225], 0, s[34:35]
	s_add_i32 m0, s47, 0xe000
	s_cmp_lg_u32 s34, 0
	global_load_lds_dwordx4 v[198:199], off
	s_waitcnt vmcnt(8)
	s_waitcnt lgkmcnt(0)
	s_add_u32 s36, s30, s34
	s_addc_u32 s37, s31, s35
	s_add_u32 s36, s36, 0x100
	s_addc_u32 s37, s37, 0
	s_add_u32 s69, s29, s34
	s_addc_u32 s70, s67, s35
	s_cmpk_eq_i32 s34, 0xf00
	s_cselect_b32 s43, s21, s37
	s_cselect_b32 s42, s27, s36
	s_cselect_b32 s37, s17, s70
	s_cselect_b32 s36, s66, s69
	s_cmp_lg_u32 s34, 0
	s_setprio 1
	s_barrier
.LBB0_807:
	v_mfma_f32_16x16x32_bf16 v[128:131], v[148:151], v[188:191], v[128:131]
	v_mfma_f32_16x16x32_bf16 v[128:131], v[152:155], v[192:195], v[128:131]
	v_mfma_f32_16x16x32_bf16 v[124:127], v[156:159], v[188:191], v[124:127]
	v_mfma_f32_16x16x32_bf16 v[124:127], v[160:163], v[192:195], v[124:127]
	v_mfma_f32_16x16x32_bf16 v[112:115], v[148:151], v[180:183], v[112:115]
	v_mfma_f32_16x16x32_bf16 v[112:115], v[152:155], v[184:187], v[112:115]
	v_mfma_f32_16x16x32_bf16 v[108:111], v[156:159], v[180:183], v[108:111]
	v_mfma_f32_16x16x32_bf16 v[108:111], v[160:163], v[184:187], v[108:111]
	v_mfma_f32_16x16x32_bf16 v[96:99], v[148:151], v[172:175], v[96:99]
	v_mfma_f32_16x16x32_bf16 v[96:99], v[152:155], v[176:179], v[96:99]
	v_mfma_f32_16x16x32_bf16 v[92:95], v[156:159], v[172:175], v[92:95]
	v_mfma_f32_16x16x32_bf16 v[92:95], v[160:163], v[176:179], v[92:95]
	v_mfma_f32_16x16x32_bf16 v[80:83], v[148:151], v[164:167], v[80:83]
	v_mfma_f32_16x16x32_bf16 v[80:83], v[152:155], v[168:171], v[80:83]
	v_mfma_f32_16x16x32_bf16 v[76:79], v[156:159], v[164:167], v[76:79]
	v_mfma_f32_16x16x32_bf16 v[76:79], v[160:163], v[168:171], v[76:79]
	v_mfma_f32_16x16x32_bf16 v[120:123], v[132:135], v[188:191], v[120:123]
	v_mfma_f32_16x16x32_bf16 v[120:123], v[136:139], v[192:195], v[120:123]
	v_mfma_f32_16x16x32_bf16 v[116:119], v[140:143], v[188:191], v[116:119]
	v_mfma_f32_16x16x32_bf16 v[116:119], v[144:147], v[192:195], v[116:119]
	v_mfma_f32_16x16x32_bf16 v[104:107], v[132:135], v[180:183], v[104:107]
	v_mfma_f32_16x16x32_bf16 v[104:107], v[136:139], v[184:187], v[104:107]
	v_mfma_f32_16x16x32_bf16 v[100:103], v[140:143], v[180:183], v[100:103]
	v_mfma_f32_16x16x32_bf16 v[100:103], v[144:147], v[184:187], v[100:103]
	v_mfma_f32_16x16x32_bf16 v[88:91], v[132:135], v[172:175], v[88:91]
	v_mfma_f32_16x16x32_bf16 v[88:91], v[136:139], v[176:179], v[88:91]
	v_mfma_f32_16x16x32_bf16 v[84:87], v[140:143], v[172:175], v[84:87]
	v_mfma_f32_16x16x32_bf16 v[84:87], v[144:147], v[176:179], v[84:87]
	v_mfma_f32_16x16x32_bf16 v[72:75], v[132:135], v[164:167], v[72:75]
	v_mfma_f32_16x16x32_bf16 v[72:75], v[136:139], v[168:171], v[72:75]
	v_mfma_f32_16x16x32_bf16 v[68:71], v[140:143], v[164:167], v[68:71]
	v_mfma_f32_16x16x32_bf16 v[68:71], v[144:147], v[168:171], v[68:71]
	s_barrier
	s_setprio 0
	s_mov_b32 m0, s52
	v_lshl_add_u64 v[198:199], s[36:37], 0, v[208:209]
	s_add_u32 s70, s36, 0x80000
	ds_read_b128 v[164:167], v240 offset:16384
	ds_read_b128 v[168:171], v240 offset:17408
	ds_read_b128 v[172:175], v240 offset:18432
	ds_read_b128 v[176:179], v240 offset:19456
	ds_read_b128 v[180:183], v240 offset:20480
	ds_read_b128 v[184:187], v240 offset:21504
	ds_read_b128 v[188:191], v240 offset:22528
	ds_read_b128 v[192:195], v240 offset:23552
	global_load_lds_dwordx4 v[198:199], off
	v_lshl_add_u64 v[200:201], s[36:37], 0, v[212:213]
	s_mov_b32 m0, s54
	s_addc_u32 s71, s37, 0
	global_load_lds_dwordx4 v[200:201], off
	v_lshl_add_u64 v[242:243], s[70:71], 0, v[208:209]
	s_mov_b32 m0, s55
	v_lshl_add_u64 v[244:245], s[42:43], 0, v[210:211]
	global_load_lds_dwordx4 v[242:243], off
	v_lshl_add_u64 v[242:243], s[70:71], 0, v[212:213]
	s_mov_b32 m0, s59
	s_nop 0
	global_load_lds_dwordx4 v[242:243], off
	v_lshl_add_u64 v[242:243], s[42:43], 0, v[206:207]
	s_mov_b32 m0, s47
	s_nop 0
	global_load_lds_dwordx4 v[242:243], off
	s_mov_b32 m0, s60
	s_nop 0
	global_load_lds_dwordx4 v[244:245], off
	s_waitcnt vmcnt(8)
	s_waitcnt lgkmcnt(0)
	s_setprio 1
	s_barrier
	v_mfma_f32_16x16x32_bf16 v[64:67], v[148:151], v[164:167], v[64:67]
	v_mfma_f32_16x16x32_bf16 v[64:67], v[152:155], v[168:171], v[64:67]
	v_mfma_f32_16x16x32_bf16 v[60:63], v[156:159], v[164:167], v[60:63]
	v_mfma_f32_16x16x32_bf16 v[60:63], v[160:163], v[168:171], v[60:63]
	v_mfma_f32_16x16x32_bf16 v[48:51], v[148:151], v[172:175], v[48:51]
	v_mfma_f32_16x16x32_bf16 v[48:51], v[152:155], v[176:179], v[48:51]
	v_mfma_f32_16x16x32_bf16 v[44:47], v[156:159], v[172:175], v[44:47]
	v_mfma_f32_16x16x32_bf16 v[44:47], v[160:163], v[176:179], v[44:47]
	v_mfma_f32_16x16x32_bf16 v[30:33], v[148:151], v[180:183], v[30:33]
	v_mfma_f32_16x16x32_bf16 v[30:33], v[152:155], v[184:187], v[30:33]
	v_mfma_f32_16x16x32_bf16 v[26:29], v[156:159], v[180:183], v[26:29]
	v_mfma_f32_16x16x32_bf16 v[26:29], v[160:163], v[184:187], v[26:29]
	v_mfma_f32_16x16x32_bf16 v[14:17], v[148:151], v[188:191], v[14:17]
	v_mfma_f32_16x16x32_bf16 v[14:17], v[152:155], v[192:195], v[14:17]
	v_mfma_f32_16x16x32_bf16 v[10:13], v[156:159], v[188:191], v[10:13]
	v_mfma_f32_16x16x32_bf16 v[10:13], v[160:163], v[192:195], v[10:13]
	v_mfma_f32_16x16x32_bf16 v[56:59], v[132:135], v[164:167], v[56:59]
	v_mfma_f32_16x16x32_bf16 v[56:59], v[136:139], v[168:171], v[56:59]
	v_mfma_f32_16x16x32_bf16 v[52:55], v[140:143], v[164:167], v[52:55]
	v_mfma_f32_16x16x32_bf16 v[52:55], v[144:147], v[168:171], v[52:55]
	v_mfma_f32_16x16x32_bf16 v[40:43], v[132:135], v[172:175], v[40:43]
	v_mfma_f32_16x16x32_bf16 v[40:43], v[136:139], v[176:179], v[40:43]
	v_mfma_f32_16x16x32_bf16 v[36:39], v[140:143], v[172:175], v[36:39]
	v_mfma_f32_16x16x32_bf16 v[36:39], v[144:147], v[176:179], v[36:39]
	v_mfma_f32_16x16x32_bf16 v[22:25], v[132:135], v[180:183], v[22:25]
	v_mfma_f32_16x16x32_bf16 v[22:25], v[136:139], v[184:187], v[22:25]
	v_mfma_f32_16x16x32_bf16 v[18:21], v[140:143], v[180:183], v[18:21]
	v_mfma_f32_16x16x32_bf16 v[18:21], v[144:147], v[184:187], v[18:21]
	v_mfma_f32_16x16x32_bf16 v[6:9], v[132:135], v[188:191], v[6:9]
	v_mfma_f32_16x16x32_bf16 v[6:9], v[136:139], v[192:195], v[6:9]
	v_mfma_f32_16x16x32_bf16 v[2:5], v[140:143], v[188:191], v[2:5]
	v_mfma_f32_16x16x32_bf16 v[2:5], v[144:147], v[192:195], v[2:5]
	s_barrier
	s_setprio 0
	s_add_i32 s69, 0, 0x18000
	v_add_u32_e32 v34, s69, v227
	s_add_i32 s70, 0, 0x1c000
	ds_read_b128 v[132:135], v34
	ds_read_b128 v[136:139], v34 offset:1024
	ds_read_b128 v[140:143], v34 offset:2048
	ds_read_b128 v[144:147], v34 offset:3072
	v_add_u32_e32 v34, s70, v227
	ds_read_b128 v[148:151], v34
	ds_read_b128 v[152:155], v34 offset:1024
	ds_read_b128 v[156:159], v34 offset:2048
	ds_read_b128 v[160:163], v34 offset:3072
	s_add_u32 s42, s42, 0x80000
	s_addc_u32 s43, s43, 0
	s_mov_b32 m0, s61
	v_lshl_add_u64 v[246:247], s[42:43], 0, v[206:207]
	ds_read_b128 v[164:167], v240 offset:32768
	ds_read_b128 v[168:171], v240 offset:33792
	ds_read_b128 v[172:175], v240 offset:34816
	ds_read_b128 v[176:179], v240 offset:35840
	ds_read_b128 v[180:183], v240 offset:36864
	ds_read_b128 v[184:187], v240 offset:37888
	ds_read_b128 v[188:191], v240 offset:38912
	ds_read_b128 v[192:195], v240 offset:39936
	global_load_lds_dwordx4 v[246:247], off
	v_lshl_add_u64 v[246:247], s[42:43], 0, v[210:211]
	s_mov_b32 m0, s62
	s_nop 0
	global_load_lds_dwordx4 v[246:247], off
	s_waitcnt vmcnt(8)
	s_waitcnt lgkmcnt(0)
	s_setprio 1
	s_barrier
	v_mfma_f32_16x16x32_bf16 v[128:131], v[132:135], v[164:167], v[128:131]
	v_mfma_f32_16x16x32_bf16 v[128:131], v[136:139], v[168:171], v[128:131]
	v_mfma_f32_16x16x32_bf16 v[124:127], v[140:143], v[164:167], v[124:127]
	v_mfma_f32_16x16x32_bf16 v[124:127], v[144:147], v[168:171], v[124:127]
	v_mfma_f32_16x16x32_bf16 v[112:115], v[132:135], v[172:175], v[112:115]
	v_mfma_f32_16x16x32_bf16 v[112:115], v[136:139], v[176:179], v[112:115]
	v_mfma_f32_16x16x32_bf16 v[108:111], v[140:143], v[172:175], v[108:111]
	v_mfma_f32_16x16x32_bf16 v[108:111], v[144:147], v[176:179], v[108:111]
	v_mfma_f32_16x16x32_bf16 v[96:99], v[132:135], v[180:183], v[96:99]
	v_mfma_f32_16x16x32_bf16 v[96:99], v[136:139], v[184:187], v[96:99]
	v_mfma_f32_16x16x32_bf16 v[92:95], v[140:143], v[180:183], v[92:95]
	v_mfma_f32_16x16x32_bf16 v[92:95], v[144:147], v[184:187], v[92:95]
	v_mfma_f32_16x16x32_bf16 v[80:83], v[132:135], v[188:191], v[80:83]
	v_mfma_f32_16x16x32_bf16 v[80:83], v[136:139], v[192:195], v[80:83]
	v_mfma_f32_16x16x32_bf16 v[76:79], v[140:143], v[188:191], v[76:79]
	v_mfma_f32_16x16x32_bf16 v[76:79], v[144:147], v[192:195], v[76:79]
	v_mfma_f32_16x16x32_bf16 v[120:123], v[148:151], v[164:167], v[120:123]
	v_mfma_f32_16x16x32_bf16 v[120:123], v[152:155], v[168:171], v[120:123]
	v_mfma_f32_16x16x32_bf16 v[116:119], v[156:159], v[164:167], v[116:119]
	v_mfma_f32_16x16x32_bf16 v[116:119], v[160:163], v[168:171], v[116:119]
	v_mfma_f32_16x16x32_bf16 v[104:107], v[148:151], v[172:175], v[104:107]
	v_mfma_f32_16x16x32_bf16 v[104:107], v[152:155], v[176:179], v[104:107]
	v_mfma_f32_16x16x32_bf16 v[100:103], v[156:159], v[172:175], v[100:103]
	v_mfma_f32_16x16x32_bf16 v[100:103], v[160:163], v[176:179], v[100:103]
	v_mfma_f32_16x16x32_bf16 v[88:91], v[148:151], v[180:183], v[88:91]
	v_mfma_f32_16x16x32_bf16 v[88:91], v[152:155], v[184:187], v[88:91]
	v_mfma_f32_16x16x32_bf16 v[84:87], v[156:159], v[180:183], v[84:87]
	v_mfma_f32_16x16x32_bf16 v[84:87], v[160:163], v[184:187], v[84:87]
	v_mfma_f32_16x16x32_bf16 v[72:75], v[148:151], v[188:191], v[72:75]
	v_mfma_f32_16x16x32_bf16 v[72:75], v[152:155], v[192:195], v[72:75]
	v_mfma_f32_16x16x32_bf16 v[68:71], v[156:159], v[188:191], v[68:71]
	v_mfma_f32_16x16x32_bf16 v[68:71], v[160:163], v[192:195], v[68:71]
	s_barrier
	s_setprio 0
	s_add_i32 s42, s69, s46
	v_lshl_add_u64 v[198:199], v[198:199], 0, s[18:19]
	s_mov_b32 m0, s42
	ds_read_b128 v[164:167], v240 offset:49152
	ds_read_b128 v[168:171], v240 offset:50176
	ds_read_b128 v[172:175], v240 offset:51200
	ds_read_b128 v[176:179], v240 offset:52224
	ds_read_b128 v[180:183], v240 offset:53248
	ds_read_b128 v[184:187], v240 offset:54272
	ds_read_b128 v[188:191], v240 offset:55296
	ds_read_b128 v[192:195], v240 offset:56320
	global_load_lds_dwordx4 v[198:199], off
	s_add_i32 m0, s42, 0x2000
	s_add_u32 s36, s36, 0x80080
	v_lshl_add_u64 v[198:199], v[200:201], 0, s[18:19]
	s_addc_u32 s37, s37, 0
	s_add_i32 s42, s70, s46
	global_load_lds_dwordx4 v[198:199], off
	v_lshl_add_u64 v[198:199], s[36:37], 0, v[208:209]
	s_mov_b32 m0, s42
	s_nop 0
	global_load_lds_dwordx4 v[198:199], off
	v_lshl_add_u64 v[198:199], s[36:37], 0, v[212:213]
	s_add_i32 m0, s42, 0x2000
	s_nop 0
	global_load_lds_dwordx4 v[198:199], off
	v_lshl_add_u64 v[198:199], v[242:243], 0, s[18:19]
	s_mov_b32 m0, s63
	s_nop 0
	global_load_lds_dwordx4 v[198:199], off
	v_lshl_add_u64 v[198:199], v[244:245], 0, s[18:19]
	s_mov_b32 m0, s64
	s_nop 0
	global_load_lds_dwordx4 v[198:199], off
	s_waitcnt vmcnt(8)
	s_waitcnt lgkmcnt(0)
	s_setprio 1
	s_barrier
	v_mfma_f32_16x16x32_bf16 v[64:67], v[132:135], v[164:167], v[64:67]
	v_mfma_f32_16x16x32_bf16 v[64:67], v[136:139], v[168:171], v[64:67]
	v_mfma_f32_16x16x32_bf16 v[60:63], v[140:143], v[164:167], v[60:63]
	v_mfma_f32_16x16x32_bf16 v[60:63], v[144:147], v[168:171], v[60:63]
	v_mfma_f32_16x16x32_bf16 v[48:51], v[132:135], v[172:175], v[48:51]
	v_mfma_f32_16x16x32_bf16 v[48:51], v[136:139], v[176:179], v[48:51]
	v_mfma_f32_16x16x32_bf16 v[44:47], v[140:143], v[172:175], v[44:47]
	v_mfma_f32_16x16x32_bf16 v[44:47], v[144:147], v[176:179], v[44:47]
	v_mfma_f32_16x16x32_bf16 v[30:33], v[132:135], v[180:183], v[30:33]
	v_mfma_f32_16x16x32_bf16 v[30:33], v[136:139], v[184:187], v[30:33]
	v_mfma_f32_16x16x32_bf16 v[26:29], v[140:143], v[180:183], v[26:29]
	v_mfma_f32_16x16x32_bf16 v[26:29], v[144:147], v[184:187], v[26:29]
	v_mfma_f32_16x16x32_bf16 v[14:17], v[132:135], v[188:191], v[14:17]
	v_mfma_f32_16x16x32_bf16 v[14:17], v[136:139], v[192:195], v[14:17]
	v_mfma_f32_16x16x32_bf16 v[10:13], v[140:143], v[188:191], v[10:13]
	v_mfma_f32_16x16x32_bf16 v[10:13], v[144:147], v[192:195], v[10:13]
	v_mfma_f32_16x16x32_bf16 v[56:59], v[148:151], v[164:167], v[56:59]
	v_mfma_f32_16x16x32_bf16 v[56:59], v[152:155], v[168:171], v[56:59]
	v_mfma_f32_16x16x32_bf16 v[52:55], v[156:159], v[164:167], v[52:55]
	v_mfma_f32_16x16x32_bf16 v[52:55], v[160:163], v[168:171], v[52:55]
	v_mfma_f32_16x16x32_bf16 v[40:43], v[148:151], v[172:175], v[40:43]
	v_mfma_f32_16x16x32_bf16 v[40:43], v[152:155], v[176:179], v[40:43]
	v_mfma_f32_16x16x32_bf16 v[36:39], v[156:159], v[172:175], v[36:39]
	v_mfma_f32_16x16x32_bf16 v[36:39], v[160:163], v[176:179], v[36:39]
	v_mfma_f32_16x16x32_bf16 v[22:25], v[148:151], v[180:183], v[22:25]
	v_mfma_f32_16x16x32_bf16 v[22:25], v[152:155], v[184:187], v[22:25]
	v_mfma_f32_16x16x32_bf16 v[18:21], v[156:159], v[180:183], v[18:21]
	v_mfma_f32_16x16x32_bf16 v[18:21], v[160:163], v[184:187], v[18:21]
	v_mfma_f32_16x16x32_bf16 v[6:9], v[148:151], v[188:191], v[6:9]
	v_mfma_f32_16x16x32_bf16 v[6:9], v[152:155], v[192:195], v[6:9]
	v_mfma_f32_16x16x32_bf16 v[2:5], v[156:159], v[188:191], v[2:5]
	v_mfma_f32_16x16x32_bf16 v[2:5], v[160:163], v[192:195], v[2:5]
	s_barrier
	s_setprio 0
	s_add_i32 s68, s68, 2
	s_add_u32 s34, s34, 0x100
	s_addc_u32 s35, s35, 0
	s_cmp_gt_u32 s68, 29
	s_cbranch_scc0 .LBB0_808
	s_branch .LBB0_810

.LBB0_891:
	s_cmp_eq_u32 s66, 28
	s_cselect_b32 s69, s21, s36
	s_cselect_b32 s68, s27, s29
	s_cselect_b32 s35, s17, s43
	s_cselect_b32 s34, s42, s37
	s_setprio 1
	s_waitcnt lgkmcnt(0)
	v_mfma_f32_16x16x32_bf16 v[64:67], v[100:103], v[124:127], v[64:67]
	v_mfma_f32_16x16x32_bf16 v[60:63], v[108:111], v[124:127], v[60:63]
	v_mfma_f32_16x16x32_bf16 v[48:51], v[100:103], v[116:119], v[48:51]
	v_mfma_f32_16x16x32_bf16 v[44:47], v[108:111], v[116:119], v[44:47]
	v_mfma_f32_16x16x32_bf16 v[30:33], v[100:103], v[92:95], v[30:33]
	v_mfma_f32_16x16x32_bf16 v[26:29], v[108:111], v[92:95], v[26:29]
	v_mfma_f32_16x16x32_bf16 v[14:17], v[100:103], v[84:87], v[14:17]
	v_mfma_f32_16x16x32_bf16 v[10:13], v[108:111], v[84:87], v[10:13]
	v_mfma_f32_16x16x32_bf16 v[64:67], v[104:107], v[128:131], v[64:67]
	v_mfma_f32_16x16x32_bf16 v[60:63], v[112:115], v[128:131], v[60:63]
	v_mfma_f32_16x16x32_bf16 v[48:51], v[104:107], v[120:123], v[48:51]
	v_mfma_f32_16x16x32_bf16 v[44:47], v[112:115], v[120:123], v[44:47]
	v_mfma_f32_16x16x32_bf16 v[30:33], v[104:107], v[96:99], v[30:33]
	v_mfma_f32_16x16x32_bf16 v[26:29], v[112:115], v[96:99], v[26:29]
	v_mfma_f32_16x16x32_bf16 v[14:17], v[104:107], v[88:91], v[14:17]
	v_mfma_f32_16x16x32_bf16 v[10:13], v[112:115], v[88:91], v[10:13]
	v_mfma_f32_16x16x32_bf16 v[56:59], v[68:71], v[124:127], v[56:59]
	v_mfma_f32_16x16x32_bf16 v[52:55], v[76:79], v[124:127], v[52:55]
	v_mfma_f32_16x16x32_bf16 v[40:43], v[68:71], v[116:119], v[40:43]
	v_mfma_f32_16x16x32_bf16 v[36:39], v[76:79], v[116:119], v[36:39]
	v_mfma_f32_16x16x32_bf16 v[22:25], v[68:71], v[92:95], v[22:25]
	v_mfma_f32_16x16x32_bf16 v[18:21], v[76:79], v[92:95], v[18:21]
	v_mfma_f32_16x16x32_bf16 v[6:9], v[68:71], v[84:87], v[6:9]
	v_mfma_f32_16x16x32_bf16 v[2:5], v[76:79], v[84:87], v[2:5]
	v_mfma_f32_16x16x32_bf16 v[56:59], v[72:75], v[128:131], v[56:59]
	v_mfma_f32_16x16x32_bf16 v[52:55], v[80:83], v[128:131], v[52:55]
	v_mfma_f32_16x16x32_bf16 v[40:43], v[72:75], v[120:123], v[40:43]
	v_mfma_f32_16x16x32_bf16 v[36:39], v[80:83], v[120:123], v[36:39]
	v_mfma_f32_16x16x32_bf16 v[22:25], v[72:75], v[96:99], v[22:25]
	v_mfma_f32_16x16x32_bf16 v[18:21], v[80:83], v[96:99], v[18:21]
	v_mfma_f32_16x16x32_bf16 v[6:9], v[72:75], v[88:91], v[6:9]
	v_mfma_f32_16x16x32_bf16 v[2:5], v[80:83], v[88:91], v[2:5]
	s_setprio 0
	s_barrier
	s_mov_b32 m0, s52
	v_lshl_add_u64 v[138:139], s[34:35], 0, v[208:209]
	s_add_u32 s70, s34, 0x80000
	global_load_lds_dwordx4 v[138:139], off
	v_lshl_add_u64 v[140:141], s[34:35], 0, v[212:213]
	s_mov_b32 m0, s54
	s_addc_u32 s71, s35, 0
	global_load_lds_dwordx4 v[140:141], off
	v_lshl_add_u64 v[68:69], s[70:71], 0, v[208:209]
	s_mov_b32 m0, s55
	v_lshl_add_u64 v[142:143], s[68:69], 0, v[206:207]
	global_load_lds_dwordx4 v[68:69], off
	v_lshl_add_u64 v[68:69], s[70:71], 0, v[212:213]
	s_mov_b32 m0, s59
	v_lshl_add_u64 v[144:145], s[68:69], 0, v[210:211]
	global_load_lds_dwordx4 v[68:69], off
	s_mov_b32 m0, s47
	s_nop 0
	global_load_lds_dwordx4 v[142:143], off
	s_mov_b32 m0, s60
	s_nop 0
	global_load_lds_dwordx4 v[144:145], off
	s_waitcnt vmcnt(6)
	s_barrier
	s_barrier
	s_add_i32 s67, 0, 0x18000
	v_add_u32_e32 v34, s67, v136
	s_add_i32 s68, 0, 0x1c000
	ds_read_b128 v[68:71], v34
	ds_read_b128 v[72:75], v34 offset:1024
	ds_read_b128 v[76:79], v34 offset:2048
	ds_read_b128 v[80:83], v34 offset:3072
	v_add_u32_e32 v34, s68, v136
	ds_read_b128 v[84:87], v34
	ds_read_b128 v[88:91], v34 offset:1024
	ds_read_b128 v[92:95], v34 offset:2048
	ds_read_b128 v[96:99], v34 offset:3072
	ds_read_b128 v[100:103], v137 offset:32768
	ds_read_b128 v[104:107], v137 offset:33792
	ds_read_b128 v[108:111], v137 offset:34816
	ds_read_b128 v[112:115], v137 offset:35840
	ds_read_b128 v[116:119], v137 offset:36864
	ds_read_b128 v[120:123], v137 offset:37888
	ds_read_b128 v[124:127], v137 offset:38912
	ds_read_b128 v[128:131], v137 offset:39936
	s_waitcnt lgkmcnt(0)
	s_barrier
	s_setprio 1
	s_waitcnt lgkmcnt(0)
	v_mfma_f32_16x16x32_bf16 v[64:67], v[68:71], v[100:103], v[64:67]
	v_mfma_f32_16x16x32_bf16 v[60:63], v[76:79], v[100:103], v[60:63]
	v_mfma_f32_16x16x32_bf16 v[48:51], v[68:71], v[108:111], v[48:51]
	v_mfma_f32_16x16x32_bf16 v[44:47], v[76:79], v[108:111], v[44:47]
	v_mfma_f32_16x16x32_bf16 v[30:33], v[68:71], v[116:119], v[30:33]
	v_mfma_f32_16x16x32_bf16 v[26:29], v[76:79], v[116:119], v[26:29]
	v_mfma_f32_16x16x32_bf16 v[14:17], v[68:71], v[124:127], v[14:17]
	v_mfma_f32_16x16x32_bf16 v[10:13], v[76:79], v[124:127], v[10:13]
	v_mfma_f32_16x16x32_bf16 v[64:67], v[72:75], v[104:107], v[64:67]
	v_mfma_f32_16x16x32_bf16 v[60:63], v[80:83], v[104:107], v[60:63]
	v_mfma_f32_16x16x32_bf16 v[48:51], v[72:75], v[112:115], v[48:51]
	v_mfma_f32_16x16x32_bf16 v[44:47], v[80:83], v[112:115], v[44:47]
	v_mfma_f32_16x16x32_bf16 v[30:33], v[72:75], v[120:123], v[30:33]
	v_mfma_f32_16x16x32_bf16 v[26:29], v[80:83], v[120:123], v[26:29]
	v_mfma_f32_16x16x32_bf16 v[14:17], v[72:75], v[128:131], v[14:17]
	v_mfma_f32_16x16x32_bf16 v[10:13], v[80:83], v[128:131], v[10:13]
	v_mfma_f32_16x16x32_bf16 v[56:59], v[84:87], v[100:103], v[56:59]
	v_mfma_f32_16x16x32_bf16 v[52:55], v[92:95], v[100:103], v[52:55]
	v_mfma_f32_16x16x32_bf16 v[40:43], v[84:87], v[108:111], v[40:43]
	v_mfma_f32_16x16x32_bf16 v[36:39], v[92:95], v[108:111], v[36:39]
	v_mfma_f32_16x16x32_bf16 v[22:25], v[84:87], v[116:119], v[22:25]
	v_mfma_f32_16x16x32_bf16 v[18:21], v[92:95], v[116:119], v[18:21]
	v_mfma_f32_16x16x32_bf16 v[6:9], v[84:87], v[124:127], v[6:9]
	v_mfma_f32_16x16x32_bf16 v[2:5], v[92:95], v[124:127], v[2:5]
	v_mfma_f32_16x16x32_bf16 v[56:59], v[88:91], v[104:107], v[56:59]
	v_mfma_f32_16x16x32_bf16 v[52:55], v[96:99], v[104:107], v[52:55]
	v_mfma_f32_16x16x32_bf16 v[40:43], v[88:91], v[112:115], v[40:43]
	v_mfma_f32_16x16x32_bf16 v[36:39], v[96:99], v[112:115], v[36:39]
	v_mfma_f32_16x16x32_bf16 v[22:25], v[88:91], v[120:123], v[22:25]
	v_mfma_f32_16x16x32_bf16 v[18:21], v[96:99], v[120:123], v[18:21]
	v_mfma_f32_16x16x32_bf16 v[6:9], v[88:91], v[128:131], v[6:9]
	v_mfma_f32_16x16x32_bf16 v[2:5], v[96:99], v[128:131], v[2:5]
	s_setprio 0
	s_barrier
	s_add_i32 s67, s67, s46
	v_lshl_add_u64 v[68:69], v[138:139], 0, s[18:19]
	s_mov_b32 m0, s67
	s_nop 0
	global_load_lds_dwordx4 v[68:69], off
	s_add_i32 m0, s67, 0x2000
	s_add_u32 s34, s34, 0x80080
	v_lshl_add_u64 v[68:69], v[140:141], 0, s[18:19]
	s_addc_u32 s35, s35, 0
	s_add_i32 s67, s68, s46
	global_load_lds_dwordx4 v[68:69], off
	v_lshl_add_u64 v[68:69], s[34:35], 0, v[208:209]
	s_mov_b32 m0, s67
	s_nop 0
	global_load_lds_dwordx4 v[68:69], off
	v_lshl_add_u64 v[68:69], s[34:35], 0, v[212:213]
	s_add_i32 m0, s67, 0x2000
	s_nop 0
	global_load_lds_dwordx4 v[68:69], off
	v_lshl_add_u64 v[68:69], v[142:143], 0, s[18:19]
	s_mov_b32 m0, s61
	s_nop 0
	global_load_lds_dwordx4 v[68:69], off
	v_lshl_add_u64 v[68:69], v[144:145], 0, s[18:19]
	s_mov_b32 m0, s62
	s_nop 0
	global_load_lds_dwordx4 v[68:69], off
	s_waitcnt vmcnt(6)
	s_barrier
	s_barrier
	s_add_i32 s66, s66, 2
	s_add_u32 s29, s29, 0x100
	s_addc_u32 s36, s36, 0
	s_add_u32 s37, s37, 0x100
	s_addc_u32 s43, s43, 0
	s_cmp_gt_u32 s66, 29
	s_cbranch_scc1 .LBB0_894

.LBB0_1429:
	s_add_i32 s46, 0, 0x10000
	s_cmp_eq_u32 s43, 2
	s_cselect_b32 s45, s13, s21
	s_cselect_b32 s44, s12, s20
	v_add_u32_e32 v34, s46, v74
	s_cselect_b32 s17, s15, s42
	s_cselect_b32 s16, s14, s39
	s_add_i32 s52, 0, 0x14000
	ds_read_b128 v[68:71], v34
	ds_read_b128 v[76:79], v34 offset:1024
	ds_read_b128 v[80:83], v34 offset:2048
	ds_read_b128 v[84:87], v34 offset:3072
	v_add_u32_e32 v34, s52, v74
	ds_read_b128 v[88:91], v34
	ds_read_b128 v[92:95], v34 offset:1024
	ds_read_b128 v[96:99], v34 offset:2048
	ds_read_b128 v[100:103], v34 offset:3072
	ds_read_b128 v[104:107], v75
	ds_read_b128 v[108:111], v75 offset:1024
	ds_read_b128 v[112:115], v75 offset:2048
	ds_read_b128 v[116:119], v75 offset:3072
	ds_read_b128 v[120:123], v75 offset:4096
	ds_read_b128 v[124:127], v75 offset:5120
	ds_read_b128 v[128:131], v75 offset:6144
	ds_read_b128 v[140:143], v75 offset:7168
	s_waitcnt lgkmcnt(0)
	s_barrier
	s_setprio 1
	s_waitcnt lgkmcnt(0)
	v_mfma_f32_16x16x32_bf16 v[64:67], v[68:71], v[104:107], v[64:67]
	v_mfma_f32_16x16x32_bf16 v[60:63], v[80:83], v[104:107], v[60:63]
	v_mfma_f32_16x16x32_bf16 v[48:51], v[68:71], v[112:115], v[48:51]
	v_mfma_f32_16x16x32_bf16 v[44:47], v[80:83], v[112:115], v[44:47]
	v_mfma_f32_16x16x32_bf16 v[30:33], v[68:71], v[120:123], v[30:33]
	v_mfma_f32_16x16x32_bf16 v[26:29], v[80:83], v[120:123], v[26:29]
	v_mfma_f32_16x16x32_bf16 v[14:17], v[68:71], v[128:131], v[14:17]
	v_mfma_f32_16x16x32_bf16 v[10:13], v[80:83], v[128:131], v[10:13]
	v_mfma_f32_16x16x32_bf16 v[64:67], v[76:79], v[108:111], v[64:67]
	v_mfma_f32_16x16x32_bf16 v[60:63], v[84:87], v[108:111], v[60:63]
	v_mfma_f32_16x16x32_bf16 v[48:51], v[76:79], v[116:119], v[48:51]
	v_mfma_f32_16x16x32_bf16 v[44:47], v[84:87], v[116:119], v[44:47]
	v_mfma_f32_16x16x32_bf16 v[30:33], v[76:79], v[124:127], v[30:33]
	v_mfma_f32_16x16x32_bf16 v[26:29], v[84:87], v[124:127], v[26:29]
	v_mfma_f32_16x16x32_bf16 v[14:17], v[76:79], v[140:143], v[14:17]
	v_mfma_f32_16x16x32_bf16 v[10:13], v[84:87], v[140:143], v[10:13]
	v_mfma_f32_16x16x32_bf16 v[56:59], v[88:91], v[104:107], v[56:59]
	v_mfma_f32_16x16x32_bf16 v[52:55], v[96:99], v[104:107], v[52:55]
	v_mfma_f32_16x16x32_bf16 v[40:43], v[88:91], v[112:115], v[40:43]
	v_mfma_f32_16x16x32_bf16 v[36:39], v[96:99], v[112:115], v[36:39]
	v_mfma_f32_16x16x32_bf16 v[22:25], v[88:91], v[120:123], v[22:25]
	v_mfma_f32_16x16x32_bf16 v[18:21], v[96:99], v[120:123], v[18:21]
	v_mfma_f32_16x16x32_bf16 v[6:9], v[88:91], v[128:131], v[6:9]
	v_mfma_f32_16x16x32_bf16 v[2:5], v[96:99], v[128:131], v[2:5]
	v_mfma_f32_16x16x32_bf16 v[56:59], v[92:95], v[108:111], v[56:59]
	v_mfma_f32_16x16x32_bf16 v[52:55], v[100:103], v[108:111], v[52:55]
	v_mfma_f32_16x16x32_bf16 v[40:43], v[92:95], v[116:119], v[40:43]
	v_mfma_f32_16x16x32_bf16 v[36:39], v[100:103], v[116:119], v[36:39]
	v_mfma_f32_16x16x32_bf16 v[22:25], v[92:95], v[124:127], v[22:25]
	v_mfma_f32_16x16x32_bf16 v[18:21], v[100:103], v[124:127], v[18:21]
	v_mfma_f32_16x16x32_bf16 v[6:9], v[92:95], v[140:143], v[6:9]
	v_mfma_f32_16x16x32_bf16 v[2:5], v[100:103], v[140:143], v[2:5]
	s_setprio 0
	s_barrier
	s_add_i32 s46, s46, s22
	v_lshl_add_u64 v[72:73], s[16:17], 0, v[134:135]
	s_mov_b32 m0, s46
	v_lshl_add_u64 v[144:145], s[16:17], 0, v[138:139]
	global_load_lds_dwordx4 v[72:73], off
	s_add_i32 m0, s46, 0x2000
	s_add_u32 s46, s16, 0x18000
	s_addc_u32 s47, s17, 0
	s_add_i32 s52, s52, s22
	global_load_lds_dwordx4 v[144:145], off
	v_lshl_add_u64 v[68:69], s[46:47], 0, v[134:135]
	s_mov_b32 m0, s52
	v_lshl_add_u64 v[146:147], s[44:45], 0, v[132:133]
	global_load_lds_dwordx4 v[68:69], off
	v_lshl_add_u64 v[68:69], s[46:47], 0, v[138:139]
	s_add_i32 m0, s52, 0x2000
	v_lshl_add_u64 v[148:149], s[44:45], 0, v[136:137]
	global_load_lds_dwordx4 v[68:69], off
	s_mov_b32 m0, s23
	s_nop 0
	global_load_lds_dwordx4 v[146:147], off
	s_mov_b32 m0, s24
	s_nop 0
	global_load_lds_dwordx4 v[148:149], off
	s_waitcnt vmcnt(6)
	s_barrier
	s_barrier
	s_add_i32 s44, 0, 0x18000
	v_add_u32_e32 v34, s44, v74
	s_add_i32 s45, 0, 0x1c000
	ds_read_b128 v[68:71], v34
	ds_read_b128 v[76:79], v34 offset:1024
	ds_read_b128 v[80:83], v34 offset:2048
	ds_read_b128 v[84:87], v34 offset:3072
	v_add_u32_e32 v34, s45, v74
	ds_read_b128 v[88:91], v34
	ds_read_b128 v[92:95], v34 offset:1024
	ds_read_b128 v[96:99], v34 offset:2048
	ds_read_b128 v[100:103], v34 offset:3072
	ds_read_b128 v[104:107], v75 offset:32768
	ds_read_b128 v[108:111], v75 offset:33792
	ds_read_b128 v[112:115], v75 offset:34816
	ds_read_b128 v[116:119], v75 offset:35840
	ds_read_b128 v[120:123], v75 offset:36864
	ds_read_b128 v[124:127], v75 offset:37888
	ds_read_b128 v[128:131], v75 offset:38912
	ds_read_b128 v[140:143], v75 offset:39936
	s_waitcnt lgkmcnt(0)
	s_barrier
	s_setprio 1
	s_waitcnt lgkmcnt(0)
	v_mfma_f32_16x16x32_bf16 v[64:67], v[68:71], v[104:107], v[64:67]
	v_mfma_f32_16x16x32_bf16 v[60:63], v[80:83], v[104:107], v[60:63]
	v_mfma_f32_16x16x32_bf16 v[48:51], v[68:71], v[112:115], v[48:51]
	v_mfma_f32_16x16x32_bf16 v[44:47], v[80:83], v[112:115], v[44:47]
	v_mfma_f32_16x16x32_bf16 v[30:33], v[68:71], v[120:123], v[30:33]
	v_mfma_f32_16x16x32_bf16 v[26:29], v[80:83], v[120:123], v[26:29]
	v_mfma_f32_16x16x32_bf16 v[14:17], v[68:71], v[128:131], v[14:17]
	v_mfma_f32_16x16x32_bf16 v[10:13], v[80:83], v[128:131], v[10:13]
	v_mfma_f32_16x16x32_bf16 v[64:67], v[76:79], v[108:111], v[64:67]
	v_mfma_f32_16x16x32_bf16 v[60:63], v[84:87], v[108:111], v[60:63]
	v_mfma_f32_16x16x32_bf16 v[48:51], v[76:79], v[116:119], v[48:51]
	v_mfma_f32_16x16x32_bf16 v[44:47], v[84:87], v[116:119], v[44:47]
	v_mfma_f32_16x16x32_bf16 v[30:33], v[76:79], v[124:127], v[30:33]
	v_mfma_f32_16x16x32_bf16 v[26:29], v[84:87], v[124:127], v[26:29]
	v_mfma_f32_16x16x32_bf16 v[14:17], v[76:79], v[140:143], v[14:17]
	v_mfma_f32_16x16x32_bf16 v[10:13], v[84:87], v[140:143], v[10:13]
	v_mfma_f32_16x16x32_bf16 v[56:59], v[88:91], v[104:107], v[56:59]
	v_mfma_f32_16x16x32_bf16 v[52:55], v[96:99], v[104:107], v[52:55]
	v_mfma_f32_16x16x32_bf16 v[40:43], v[88:91], v[112:115], v[40:43]
	v_mfma_f32_16x16x32_bf16 v[36:39], v[96:99], v[112:115], v[36:39]
	v_mfma_f32_16x16x32_bf16 v[22:25], v[88:91], v[120:123], v[22:25]
	v_mfma_f32_16x16x32_bf16 v[18:21], v[96:99], v[120:123], v[18:21]
	v_mfma_f32_16x16x32_bf16 v[6:9], v[88:91], v[128:131], v[6:9]
	v_mfma_f32_16x16x32_bf16 v[2:5], v[96:99], v[128:131], v[2:5]
	v_mfma_f32_16x16x32_bf16 v[56:59], v[92:95], v[108:111], v[56:59]
	v_mfma_f32_16x16x32_bf16 v[52:55], v[100:103], v[108:111], v[52:55]
	v_mfma_f32_16x16x32_bf16 v[40:43], v[92:95], v[116:119], v[40:43]
	v_mfma_f32_16x16x32_bf16 v[36:39], v[100:103], v[116:119], v[36:39]
	v_mfma_f32_16x16x32_bf16 v[22:25], v[92:95], v[124:127], v[22:25]
	v_mfma_f32_16x16x32_bf16 v[18:21], v[100:103], v[124:127], v[18:21]
	v_mfma_f32_16x16x32_bf16 v[6:9], v[92:95], v[140:143], v[6:9]
	v_mfma_f32_16x16x32_bf16 v[2:5], v[100:103], v[140:143], v[2:5]
	s_setprio 0
	s_barrier
	s_add_i32 s44, s44, s22
	v_lshl_add_u64 v[68:69], v[72:73], 0, s[18:19]
	s_mov_b32 m0, s44
	s_nop 0
	global_load_lds_dwordx4 v[68:69], off
	s_add_i32 m0, s44, 0x2000
	s_add_u32 s16, s16, 0x18080
	v_lshl_add_u64 v[68:69], v[144:145], 0, s[18:19]
	s_addc_u32 s17, s17, 0
	s_add_i32 s44, s45, s22
	global_load_lds_dwordx4 v[68:69], off
	v_lshl_add_u64 v[68:69], s[16:17], 0, v[134:135]
	s_mov_b32 m0, s44
	s_nop 0
	global_load_lds_dwordx4 v[68:69], off
	v_lshl_add_u64 v[68:69], s[16:17], 0, v[138:139]
	s_add_i32 m0, s44, 0x2000
	s_nop 0
	global_load_lds_dwordx4 v[68:69], off
	v_lshl_add_u64 v[68:69], v[146:147], 0, s[18:19]
	s_mov_b32 m0, s25
	s_nop 0
	global_load_lds_dwordx4 v[68:69], off
	v_lshl_add_u64 v[68:69], v[148:149], 0, s[18:19]
	s_mov_b32 m0, s30
	s_nop 0
	global_load_lds_dwordx4 v[68:69], off
	s_waitcnt vmcnt(6)
	s_barrier
	s_barrier
	s_add_i32 s43, s43, 2
	s_add_u32 s20, s20, 0x100
	s_addc_u32 s21, s21, 0
	s_add_u32 s39, s39, 0x100
	s_addc_u32 s42, s42, 0
	s_cmp_gt_u32 s43, 3
	s_cbranch_scc0 .LBB0_1429
	s_and_b64 vcc, exec, s[10:11]
	s_cbranch_vccz .LBB0_1432
	s_barrier

.LBB0_1553:
	s_add_i32 s61, 0, 0x10000
	s_cmp_eq_u32 s60, 12
	s_cselect_b32 s63, s15, s37
	s_cselect_b32 s62, s17, s36
	s_cselect_b32 s35, s25, s43
	s_cselect_b32 s34, s27, s42
	s_add_i32 s66, 0, 0x14000
	v_add_u32_e32 v80, s61, v98
	v_add_u32_e32 v96, s66, v98
	ds_read_b128 v[68:71], v80
	ds_read_b128 v[72:75], v80 offset:1024
	ds_read_b128 v[76:79], v80 offset:2048
	ds_read_b128 v[80:83], v80 offset:3072
	ds_read_b128 v[84:87], v96
	ds_read_b128 v[88:91], v96 offset:1024
	ds_read_b128 v[92:95], v96 offset:2048
	ds_read_b128 v[100:103], v96 offset:3072
	ds_read_b128 v[104:107], v99
	ds_read_b128 v[108:111], v99 offset:1024
	ds_read_b128 v[112:115], v99 offset:2048
	ds_read_b128 v[116:119], v99 offset:3072
	ds_read_b128 v[120:123], v99 offset:4096
	ds_read_b128 v[124:127], v99 offset:5120
	ds_read_b128 v[128:131], v99 offset:6144
	ds_read_b128 v[132:135], v99 offset:7168
	s_waitcnt lgkmcnt(0)
	s_barrier
	s_setprio 1
	s_waitcnt lgkmcnt(0)
	v_mfma_f32_16x16x32_bf16 v[60:63], v[68:71], v[104:107], v[60:63]
	v_mfma_f32_16x16x32_bf16 v[48:51], v[76:79], v[104:107], v[48:51]
	v_mfma_f32_16x16x32_bf16 v[52:55], v[68:71], v[112:115], v[52:55]
	v_mfma_f32_16x16x32_bf16 v[44:47], v[76:79], v[112:115], v[44:47]
	v_mfma_f32_16x16x32_bf16 v[30:33], v[68:71], v[120:123], v[30:33]
	v_mfma_f32_16x16x32_bf16 v[26:29], v[76:79], v[120:123], v[26:29]
	v_mfma_f32_16x16x32_bf16 v[14:17], v[68:71], v[128:131], v[14:17]
	v_mfma_f32_16x16x32_bf16 v[10:13], v[76:79], v[128:131], v[10:13]
	v_mfma_f32_16x16x32_bf16 v[60:63], v[72:75], v[108:111], v[60:63]
	v_mfma_f32_16x16x32_bf16 v[48:51], v[80:83], v[108:111], v[48:51]
	v_mfma_f32_16x16x32_bf16 v[52:55], v[72:75], v[116:119], v[52:55]
	v_mfma_f32_16x16x32_bf16 v[44:47], v[80:83], v[116:119], v[44:47]
	v_mfma_f32_16x16x32_bf16 v[30:33], v[72:75], v[124:127], v[30:33]
	v_mfma_f32_16x16x32_bf16 v[26:29], v[80:83], v[124:127], v[26:29]
	v_mfma_f32_16x16x32_bf16 v[14:17], v[72:75], v[132:135], v[14:17]
	v_mfma_f32_16x16x32_bf16 v[10:13], v[80:83], v[132:135], v[10:13]
	v_mfma_f32_16x16x32_bf16 v[64:67], v[84:87], v[104:107], v[64:67]
	v_mfma_f32_16x16x32_bf16 v[56:59], v[92:95], v[104:107], v[56:59]
	v_mfma_f32_16x16x32_bf16 v[40:43], v[84:87], v[112:115], v[40:43]
	v_mfma_f32_16x16x32_bf16 v[36:39], v[92:95], v[112:115], v[36:39]
	v_mfma_f32_16x16x32_bf16 v[22:25], v[84:87], v[120:123], v[22:25]
	v_mfma_f32_16x16x32_bf16 v[18:21], v[92:95], v[120:123], v[18:21]
	v_mfma_f32_16x16x32_bf16 v[6:9], v[84:87], v[128:131], v[6:9]
	v_mfma_f32_16x16x32_bf16 v[2:5], v[92:95], v[128:131], v[2:5]
	v_mfma_f32_16x16x32_bf16 v[64:67], v[88:91], v[108:111], v[64:67]
	v_mfma_f32_16x16x32_bf16 v[56:59], v[100:103], v[108:111], v[56:59]
	v_mfma_f32_16x16x32_bf16 v[40:43], v[88:91], v[116:119], v[40:43]
	v_mfma_f32_16x16x32_bf16 v[36:39], v[100:103], v[116:119], v[36:39]
	v_mfma_f32_16x16x32_bf16 v[22:25], v[88:91], v[124:127], v[22:25]
	v_mfma_f32_16x16x32_bf16 v[18:21], v[100:103], v[124:127], v[18:21]
	v_mfma_f32_16x16x32_bf16 v[6:9], v[88:91], v[132:135], v[6:9]
	v_mfma_f32_16x16x32_bf16 v[2:5], v[100:103], v[132:135], v[2:5]
	s_setprio 0
	s_barrier
	s_add_i32 s61, s61, s44
	v_lshl_add_u64 v[96:97], s[34:35], 0, v[34:35]
	s_mov_b32 m0, s61
	v_lshl_add_u64 v[136:137], s[34:35], 0, v[152:153]
	global_load_lds_dwordx4 v[96:97], off
	s_add_i32 m0, s61, 0x2000
	s_add_u32 s64, s34, 0x40000
	s_addc_u32 s65, s35, 0
	s_add_i32 s61, s66, s44
	global_load_lds_dwordx4 v[136:137], off
	v_lshl_add_u64 v[68:69], s[64:65], 0, v[34:35]
	s_mov_b32 m0, s61
	v_lshl_add_u64 v[138:139], s[62:63], 0, v[148:149]
	global_load_lds_dwordx4 v[68:69], off
	v_lshl_add_u64 v[68:69], s[64:65], 0, v[152:153]
	s_add_i32 m0, s61, 0x2000
	v_lshl_add_u64 v[140:141], s[62:63], 0, v[150:151]
	global_load_lds_dwordx4 v[68:69], off
	s_mov_b32 m0, s45
	s_nop 0
	global_load_lds_dwordx4 v[138:139], off
	s_mov_b32 m0, s46
	s_nop 0
	global_load_lds_dwordx4 v[140:141], off
	s_waitcnt vmcnt(6)
	s_barrier
	s_barrier
	s_add_i32 s61, 0, 0x18000
	s_add_i32 s62, 0, 0x1c000
	v_add_u32_e32 v80, s61, v98
	v_add_u32_e32 v100, s62, v98
	ds_read_b128 v[68:71], v80
	ds_read_b128 v[72:75], v80 offset:1024
	ds_read_b128 v[76:79], v80 offset:2048
	ds_read_b128 v[80:83], v80 offset:3072
	ds_read_b128 v[84:87], v100
	ds_read_b128 v[88:91], v100 offset:1024
	ds_read_b128 v[92:95], v100 offset:2048
	ds_read_b128 v[100:103], v100 offset:3072
	ds_read_b128 v[104:107], v99 offset:32768
	ds_read_b128 v[108:111], v99 offset:33792
	ds_read_b128 v[112:115], v99 offset:34816
	ds_read_b128 v[116:119], v99 offset:35840
	ds_read_b128 v[120:123], v99 offset:36864
	ds_read_b128 v[124:127], v99 offset:37888
	ds_read_b128 v[128:131], v99 offset:38912
	ds_read_b128 v[132:135], v99 offset:39936
	s_waitcnt lgkmcnt(0)
	s_barrier
	s_setprio 1
	s_waitcnt lgkmcnt(0)
	v_mfma_f32_16x16x32_bf16 v[60:63], v[68:71], v[104:107], v[60:63]
	v_mfma_f32_16x16x32_bf16 v[48:51], v[76:79], v[104:107], v[48:51]
	v_mfma_f32_16x16x32_bf16 v[52:55], v[68:71], v[112:115], v[52:55]
	v_mfma_f32_16x16x32_bf16 v[44:47], v[76:79], v[112:115], v[44:47]
	v_mfma_f32_16x16x32_bf16 v[30:33], v[68:71], v[120:123], v[30:33]
	v_mfma_f32_16x16x32_bf16 v[26:29], v[76:79], v[120:123], v[26:29]
	v_mfma_f32_16x16x32_bf16 v[14:17], v[68:71], v[128:131], v[14:17]
	v_mfma_f32_16x16x32_bf16 v[10:13], v[76:79], v[128:131], v[10:13]
	v_mfma_f32_16x16x32_bf16 v[60:63], v[72:75], v[108:111], v[60:63]
	v_mfma_f32_16x16x32_bf16 v[48:51], v[80:83], v[108:111], v[48:51]
	v_mfma_f32_16x16x32_bf16 v[52:55], v[72:75], v[116:119], v[52:55]
	v_mfma_f32_16x16x32_bf16 v[44:47], v[80:83], v[116:119], v[44:47]
	v_mfma_f32_16x16x32_bf16 v[30:33], v[72:75], v[124:127], v[30:33]
	v_mfma_f32_16x16x32_bf16 v[26:29], v[80:83], v[124:127], v[26:29]
	v_mfma_f32_16x16x32_bf16 v[14:17], v[72:75], v[132:135], v[14:17]
	v_mfma_f32_16x16x32_bf16 v[10:13], v[80:83], v[132:135], v[10:13]
	v_mfma_f32_16x16x32_bf16 v[64:67], v[84:87], v[104:107], v[64:67]
	v_mfma_f32_16x16x32_bf16 v[56:59], v[92:95], v[104:107], v[56:59]
	v_mfma_f32_16x16x32_bf16 v[40:43], v[84:87], v[112:115], v[40:43]
	v_mfma_f32_16x16x32_bf16 v[36:39], v[92:95], v[112:115], v[36:39]
	v_mfma_f32_16x16x32_bf16 v[22:25], v[84:87], v[120:123], v[22:25]
	v_mfma_f32_16x16x32_bf16 v[18:21], v[92:95], v[120:123], v[18:21]
	v_mfma_f32_16x16x32_bf16 v[6:9], v[84:87], v[128:131], v[6:9]
	v_mfma_f32_16x16x32_bf16 v[2:5], v[92:95], v[128:131], v[2:5]
	v_mfma_f32_16x16x32_bf16 v[64:67], v[88:91], v[108:111], v[64:67]
	v_mfma_f32_16x16x32_bf16 v[56:59], v[100:103], v[108:111], v[56:59]
	v_mfma_f32_16x16x32_bf16 v[40:43], v[88:91], v[116:119], v[40:43]
	v_mfma_f32_16x16x32_bf16 v[36:39], v[100:103], v[116:119], v[36:39]
	v_mfma_f32_16x16x32_bf16 v[22:25], v[88:91], v[124:127], v[22:25]
	v_mfma_f32_16x16x32_bf16 v[18:21], v[100:103], v[124:127], v[18:21]
	v_mfma_f32_16x16x32_bf16 v[6:9], v[88:91], v[132:135], v[6:9]
	v_mfma_f32_16x16x32_bf16 v[2:5], v[100:103], v[132:135], v[2:5]
	s_setprio 0
	s_barrier
	s_add_i32 s61, s61, s44
	v_lshl_add_u64 v[68:69], v[96:97], 0, s[18:19]
	s_mov_b32 m0, s61
	s_nop 0
	global_load_lds_dwordx4 v[68:69], off
	s_add_i32 m0, s61, 0x2000
	s_add_u32 s34, s34, 0x40080
	v_lshl_add_u64 v[68:69], v[136:137], 0, s[18:19]
	s_addc_u32 s35, s35, 0
	s_add_i32 s61, s62, s44
	global_load_lds_dwordx4 v[68:69], off
	v_lshl_add_u64 v[68:69], s[34:35], 0, v[34:35]
	s_mov_b32 m0, s61
	s_nop 0
	global_load_lds_dwordx4 v[68:69], off
	v_lshl_add_u64 v[68:69], s[34:35], 0, v[152:153]
	s_add_i32 m0, s61, 0x2000
	s_nop 0
	global_load_lds_dwordx4 v[68:69], off
	v_lshl_add_u64 v[68:69], v[138:139], 0, s[18:19]
	s_mov_b32 m0, s47
	s_nop 0
	global_load_lds_dwordx4 v[68:69], off
	v_lshl_add_u64 v[68:69], v[140:141], 0, s[18:19]
	s_mov_b32 m0, s54
	s_nop 0
	global_load_lds_dwordx4 v[68:69], off
	s_waitcnt vmcnt(6)
	s_barrier
	s_barrier
	s_add_i32 s60, s60, 2
	s_add_u32 s36, s36, 0x100
	s_addc_u32 s37, s37, 0
	s_add_u32 s42, s42, 0x100
	s_addc_u32 s43, s43, 0
	s_cmp_gt_u32 s60, 13
	s_cbranch_scc0 .LBB0_1553
	s_and_b64 vcc, exec, s[22:23]
	s_cbranch_vccz .LBB0_1556
	s_barrier

.LBB0_1646:
	v_add_u32_e32 v34, 0, v242
	v_add_u32_e32 v36, 0x10000, v34
	v_add_u32_e32 v34, 0x14000, v34
	ds_read_b128 v[150:153], v36
	ds_read_b128 v[154:157], v36 offset:1024
	ds_read_b128 v[158:161], v36 offset:2048
	ds_read_b128 v[162:165], v36 offset:3072
	ds_read_b128 v[134:137], v34
	ds_read_b128 v[138:141], v34 offset:1024
	ds_read_b128 v[142:145], v34 offset:2048
	ds_read_b128 v[146:149], v34 offset:3072
	v_lshl_add_u64 v[36:37], v[224:225], 0, s[36:37]
	s_add_i32 m0, s54, 0xc000
	ds_read_b128 v[190:193], v244
	ds_read_b128 v[194:197], v244 offset:1024
	ds_read_b128 v[182:185], v244 offset:2048
	ds_read_b128 v[186:189], v244 offset:3072
	ds_read_b128 v[174:177], v244 offset:4096
	ds_read_b128 v[178:181], v244 offset:5120
	ds_read_b128 v[166:169], v244 offset:6144
	ds_read_b128 v[170:173], v244 offset:7168
	global_load_lds_dwordx4 v[36:37], off
	v_lshl_add_u64 v[36:37], v[226:227], 0, s[36:37]
	s_add_i32 m0, s54, 0xe000
	s_cmp_lg_u32 s36, 0
	global_load_lds_dwordx4 v[36:37], off
	s_waitcnt vmcnt(8)
	s_waitcnt lgkmcnt(0)
	s_add_u32 s40, s34, s36
	s_addc_u32 s41, s35, s37
	s_add_u32 s40, s40, 0x100
	s_addc_u32 s41, s41, 0
	s_add_u32 s78, s31, s36
	s_addc_u32 s79, s77, s37
	s_cmpk_eq_i32 s36, 0xf00
	s_cselect_b32 s43, s13, s41
	s_cselect_b32 s42, s23, s40
	s_cselect_b32 s41, s21, s79
	s_cselect_b32 s40, s76, s78
	s_cmp_lg_u32 s36, 0
	s_setprio 1
	s_barrier
.LBB0_1643:
	v_mfma_f32_16x16x32_bf16 v[130:133], v[150:153], v[190:193], v[130:133]
	v_mfma_f32_16x16x32_bf16 v[130:133], v[154:157], v[194:197], v[130:133]
	v_mfma_f32_16x16x32_bf16 v[126:129], v[158:161], v[190:193], v[126:129]
	v_mfma_f32_16x16x32_bf16 v[126:129], v[162:165], v[194:197], v[126:129]
	v_mfma_f32_16x16x32_bf16 v[114:117], v[150:153], v[182:185], v[114:117]
	v_mfma_f32_16x16x32_bf16 v[114:117], v[154:157], v[186:189], v[114:117]
	v_mfma_f32_16x16x32_bf16 v[110:113], v[158:161], v[182:185], v[110:113]
	v_mfma_f32_16x16x32_bf16 v[110:113], v[162:165], v[186:189], v[110:113]
	v_mfma_f32_16x16x32_bf16 v[98:101], v[150:153], v[174:177], v[98:101]
	v_mfma_f32_16x16x32_bf16 v[98:101], v[154:157], v[178:181], v[98:101]
	v_mfma_f32_16x16x32_bf16 v[94:97], v[158:161], v[174:177], v[94:97]
	v_mfma_f32_16x16x32_bf16 v[94:97], v[162:165], v[178:181], v[94:97]
	v_mfma_f32_16x16x32_bf16 v[82:85], v[150:153], v[166:169], v[82:85]
	v_mfma_f32_16x16x32_bf16 v[82:85], v[154:157], v[170:173], v[82:85]
	v_mfma_f32_16x16x32_bf16 v[78:81], v[158:161], v[166:169], v[78:81]
	v_mfma_f32_16x16x32_bf16 v[78:81], v[162:165], v[170:173], v[78:81]
	v_mfma_f32_16x16x32_bf16 v[122:125], v[134:137], v[190:193], v[122:125]
	v_mfma_f32_16x16x32_bf16 v[122:125], v[138:141], v[194:197], v[122:125]
	v_mfma_f32_16x16x32_bf16 v[118:121], v[142:145], v[190:193], v[118:121]
	v_mfma_f32_16x16x32_bf16 v[118:121], v[146:149], v[194:197], v[118:121]
	v_mfma_f32_16x16x32_bf16 v[106:109], v[134:137], v[182:185], v[106:109]
	v_mfma_f32_16x16x32_bf16 v[106:109], v[138:141], v[186:189], v[106:109]
	v_mfma_f32_16x16x32_bf16 v[102:105], v[142:145], v[182:185], v[102:105]
	v_mfma_f32_16x16x32_bf16 v[102:105], v[146:149], v[186:189], v[102:105]
	v_mfma_f32_16x16x32_bf16 v[90:93], v[134:137], v[174:177], v[90:93]
	v_mfma_f32_16x16x32_bf16 v[90:93], v[138:141], v[178:181], v[90:93]
	v_mfma_f32_16x16x32_bf16 v[86:89], v[142:145], v[174:177], v[86:89]
	v_mfma_f32_16x16x32_bf16 v[86:89], v[146:149], v[178:181], v[86:89]
	v_mfma_f32_16x16x32_bf16 v[74:77], v[134:137], v[166:169], v[74:77]
	v_mfma_f32_16x16x32_bf16 v[74:77], v[138:141], v[170:173], v[74:77]
	v_mfma_f32_16x16x32_bf16 v[70:73], v[142:145], v[166:169], v[70:73]
	v_mfma_f32_16x16x32_bf16 v[70:73], v[146:149], v[170:173], v[70:73]
	s_barrier
	s_setprio 0
	s_mov_b32 m0, s55
	v_lshl_add_u64 v[198:199], s[40:41], 0, v[210:211]
	s_add_u32 s78, s40, 0x80000
	ds_read_b128 v[166:169], v244 offset:16384
	ds_read_b128 v[170:173], v244 offset:17408
	ds_read_b128 v[174:177], v244 offset:18432
	ds_read_b128 v[178:181], v244 offset:19456
	ds_read_b128 v[182:185], v244 offset:20480
	ds_read_b128 v[186:189], v244 offset:21504
	ds_read_b128 v[190:193], v244 offset:22528
	ds_read_b128 v[194:197], v244 offset:23552
	global_load_lds_dwordx4 v[198:199], off
	v_lshl_add_u64 v[200:201], s[40:41], 0, v[214:215]
	s_mov_b32 m0, s59
	s_addc_u32 s79, s41, 0
	global_load_lds_dwordx4 v[200:201], off
	v_lshl_add_u64 v[36:37], s[78:79], 0, v[210:211]
	s_mov_b32 m0, s60
	v_lshl_add_u64 v[246:247], s[42:43], 0, v[208:209]
	global_load_lds_dwordx4 v[36:37], off
	v_lshl_add_u64 v[36:37], s[78:79], 0, v[214:215]
	s_mov_b32 m0, s61
	v_lshl_add_u64 v[248:249], s[42:43], 0, v[212:213]
	global_load_lds_dwordx4 v[36:37], off
	s_mov_b32 m0, s54
	s_nop 0
	global_load_lds_dwordx4 v[246:247], off
	s_mov_b32 m0, s62
	s_nop 0
	global_load_lds_dwordx4 v[248:249], off
	s_waitcnt vmcnt(8)
	s_waitcnt lgkmcnt(0)
	s_setprio 1
	s_barrier
	v_mfma_f32_16x16x32_bf16 v[66:69], v[150:153], v[166:169], v[66:69]
	v_mfma_f32_16x16x32_bf16 v[66:69], v[154:157], v[170:173], v[66:69]
	v_mfma_f32_16x16x32_bf16 v[62:65], v[158:161], v[166:169], v[62:65]
	v_mfma_f32_16x16x32_bf16 v[62:65], v[162:165], v[170:173], v[62:65]
	v_mfma_f32_16x16x32_bf16 v[50:53], v[150:153], v[174:177], v[50:53]
	v_mfma_f32_16x16x32_bf16 v[50:53], v[154:157], v[178:181], v[50:53]
	v_mfma_f32_16x16x32_bf16 v[46:49], v[158:161], v[174:177], v[46:49]
	v_mfma_f32_16x16x32_bf16 v[46:49], v[162:165], v[178:181], v[46:49]
	v_mfma_f32_16x16x32_bf16 v[30:33], v[150:153], v[182:185], v[30:33]
	v_mfma_f32_16x16x32_bf16 v[30:33], v[154:157], v[186:189], v[30:33]
	v_mfma_f32_16x16x32_bf16 v[26:29], v[158:161], v[182:185], v[26:29]
	v_mfma_f32_16x16x32_bf16 v[26:29], v[162:165], v[186:189], v[26:29]
	v_mfma_f32_16x16x32_bf16 v[14:17], v[150:153], v[190:193], v[14:17]
	v_mfma_f32_16x16x32_bf16 v[14:17], v[154:157], v[194:197], v[14:17]
	v_mfma_f32_16x16x32_bf16 v[10:13], v[158:161], v[190:193], v[10:13]
	v_mfma_f32_16x16x32_bf16 v[10:13], v[162:165], v[194:197], v[10:13]
	v_mfma_f32_16x16x32_bf16 v[58:61], v[134:137], v[166:169], v[58:61]
	v_mfma_f32_16x16x32_bf16 v[58:61], v[138:141], v[170:173], v[58:61]
	v_mfma_f32_16x16x32_bf16 v[54:57], v[142:145], v[166:169], v[54:57]
	v_mfma_f32_16x16x32_bf16 v[54:57], v[146:149], v[170:173], v[54:57]
	v_mfma_f32_16x16x32_bf16 v[42:45], v[134:137], v[174:177], v[42:45]
	v_mfma_f32_16x16x32_bf16 v[42:45], v[138:141], v[178:181], v[42:45]
	v_mfma_f32_16x16x32_bf16 v[36:39], v[142:145], v[174:177], v[38:41]
	v_mfma_f32_16x16x32_bf16 v[36:39], v[146:149], v[178:181], v[36:39]
	v_mfma_f32_16x16x32_bf16 v[22:25], v[134:137], v[182:185], v[22:25]
	v_mfma_f32_16x16x32_bf16 v[22:25], v[138:141], v[186:189], v[22:25]
	v_mfma_f32_16x16x32_bf16 v[18:21], v[142:145], v[182:185], v[18:21]
	v_mfma_f32_16x16x32_bf16 v[18:21], v[146:149], v[186:189], v[18:21]
	v_mfma_f32_16x16x32_bf16 v[6:9], v[134:137], v[190:193], v[6:9]
	v_mfma_f32_16x16x32_bf16 v[6:9], v[138:141], v[194:197], v[6:9]
	v_mfma_f32_16x16x32_bf16 v[2:5], v[142:145], v[190:193], v[2:5]
	v_mfma_f32_16x16x32_bf16 v[2:5], v[146:149], v[194:197], v[2:5]
	s_barrier
	s_setprio 0
	s_add_i32 s78, 0, 0x18000
	v_add_u32_e32 v34, s78, v242
	s_add_i32 s79, 0, 0x1c000
	ds_read_b128 v[134:137], v34
	ds_read_b128 v[138:141], v34 offset:1024
	ds_read_b128 v[142:145], v34 offset:2048
	ds_read_b128 v[146:149], v34 offset:3072
	v_add_u32_e32 v34, s79, v242
	ds_read_b128 v[150:153], v34
	ds_read_b128 v[154:157], v34 offset:1024
	ds_read_b128 v[158:161], v34 offset:2048
	ds_read_b128 v[162:165], v34 offset:3072
	s_add_u32 s42, s42, 0x80000
	s_addc_u32 s43, s43, 0
	s_mov_b32 m0, s63
	v_lshl_add_u64 v[40:41], s[42:43], 0, v[208:209]
	ds_read_b128 v[166:169], v244 offset:32768
	ds_read_b128 v[170:173], v244 offset:33792
	ds_read_b128 v[174:177], v244 offset:34816
	ds_read_b128 v[178:181], v244 offset:35840
	ds_read_b128 v[182:185], v244 offset:36864
	ds_read_b128 v[186:189], v244 offset:37888
	ds_read_b128 v[190:193], v244 offset:38912
	ds_read_b128 v[194:197], v244 offset:39936
	global_load_lds_dwordx4 v[40:41], off
	v_lshl_add_u64 v[40:41], s[42:43], 0, v[212:213]
	s_mov_b32 m0, s64
	s_nop 0
	global_load_lds_dwordx4 v[40:41], off
	s_waitcnt vmcnt(8)
	s_waitcnt lgkmcnt(0)
	s_setprio 1
	s_barrier
	v_mfma_f32_16x16x32_bf16 v[130:133], v[134:137], v[166:169], v[130:133]
	v_mfma_f32_16x16x32_bf16 v[130:133], v[138:141], v[170:173], v[130:133]
	v_mfma_f32_16x16x32_bf16 v[126:129], v[142:145], v[166:169], v[126:129]
	v_mfma_f32_16x16x32_bf16 v[126:129], v[146:149], v[170:173], v[126:129]
	v_mfma_f32_16x16x32_bf16 v[114:117], v[134:137], v[174:177], v[114:117]
	v_mfma_f32_16x16x32_bf16 v[114:117], v[138:141], v[178:181], v[114:117]
	v_mfma_f32_16x16x32_bf16 v[110:113], v[142:145], v[174:177], v[110:113]
	v_mfma_f32_16x16x32_bf16 v[110:113], v[146:149], v[178:181], v[110:113]
	v_mfma_f32_16x16x32_bf16 v[98:101], v[134:137], v[182:185], v[98:101]
	v_mfma_f32_16x16x32_bf16 v[98:101], v[138:141], v[186:189], v[98:101]
	v_mfma_f32_16x16x32_bf16 v[94:97], v[142:145], v[182:185], v[94:97]
	v_mfma_f32_16x16x32_bf16 v[94:97], v[146:149], v[186:189], v[94:97]
	v_mfma_f32_16x16x32_bf16 v[82:85], v[134:137], v[190:193], v[82:85]
	v_mfma_f32_16x16x32_bf16 v[82:85], v[138:141], v[194:197], v[82:85]
	v_mfma_f32_16x16x32_bf16 v[78:81], v[142:145], v[190:193], v[78:81]
	v_mfma_f32_16x16x32_bf16 v[78:81], v[146:149], v[194:197], v[78:81]
	v_mfma_f32_16x16x32_bf16 v[122:125], v[150:153], v[166:169], v[122:125]
	v_mfma_f32_16x16x32_bf16 v[122:125], v[154:157], v[170:173], v[122:125]
	v_mfma_f32_16x16x32_bf16 v[118:121], v[158:161], v[166:169], v[118:121]
	v_mfma_f32_16x16x32_bf16 v[118:121], v[162:165], v[170:173], v[118:121]
	v_mfma_f32_16x16x32_bf16 v[106:109], v[150:153], v[174:177], v[106:109]
	v_mfma_f32_16x16x32_bf16 v[106:109], v[154:157], v[178:181], v[106:109]
	v_mfma_f32_16x16x32_bf16 v[102:105], v[158:161], v[174:177], v[102:105]
	v_mfma_f32_16x16x32_bf16 v[102:105], v[162:165], v[178:181], v[102:105]
	v_mfma_f32_16x16x32_bf16 v[90:93], v[150:153], v[182:185], v[90:93]
	v_mfma_f32_16x16x32_bf16 v[90:93], v[154:157], v[186:189], v[90:93]
	v_mfma_f32_16x16x32_bf16 v[86:89], v[158:161], v[182:185], v[86:89]
	v_mfma_f32_16x16x32_bf16 v[86:89], v[162:165], v[186:189], v[86:89]
	v_mfma_f32_16x16x32_bf16 v[74:77], v[150:153], v[190:193], v[74:77]
	v_mfma_f32_16x16x32_bf16 v[74:77], v[154:157], v[194:197], v[74:77]
	v_mfma_f32_16x16x32_bf16 v[70:73], v[158:161], v[190:193], v[70:73]
	v_mfma_f32_16x16x32_bf16 v[70:73], v[162:165], v[194:197], v[70:73]
	s_barrier
	s_setprio 0
	s_add_i32 s42, s78, s52
	v_lshl_add_u64 v[40:41], v[198:199], 0, s[18:19]
	s_mov_b32 m0, s42
	ds_read_b128 v[166:169], v244 offset:49152
	ds_read_b128 v[170:173], v244 offset:50176
	ds_read_b128 v[174:177], v244 offset:51200
	ds_read_b128 v[178:181], v244 offset:52224
	ds_read_b128 v[182:185], v244 offset:53248
	ds_read_b128 v[186:189], v244 offset:54272
	ds_read_b128 v[190:193], v244 offset:55296
	ds_read_b128 v[194:197], v244 offset:56320
	global_load_lds_dwordx4 v[40:41], off
	s_add_i32 m0, s42, 0x2000
	s_add_u32 s40, s40, 0x80080
	v_lshl_add_u64 v[40:41], v[200:201], 0, s[18:19]
	s_addc_u32 s41, s41, 0
	s_add_i32 s42, s79, s52
	global_load_lds_dwordx4 v[40:41], off
	v_lshl_add_u64 v[40:41], s[40:41], 0, v[210:211]
	s_mov_b32 m0, s42
	s_nop 0
	global_load_lds_dwordx4 v[40:41], off
	v_lshl_add_u64 v[40:41], s[40:41], 0, v[214:215]
	s_add_i32 m0, s42, 0x2000
	s_nop 0
	global_load_lds_dwordx4 v[40:41], off
	v_lshl_add_u64 v[40:41], v[246:247], 0, s[18:19]
	s_mov_b32 m0, s65
	s_nop 0
	global_load_lds_dwordx4 v[40:41], off
	v_lshl_add_u64 v[40:41], v[248:249], 0, s[18:19]
	s_mov_b32 m0, s66
	s_nop 0
	global_load_lds_dwordx4 v[40:41], off
	s_waitcnt vmcnt(8)
	s_waitcnt lgkmcnt(0)
	s_setprio 1
	s_barrier
	v_mfma_f32_16x16x32_bf16 v[66:69], v[134:137], v[166:169], v[66:69]
	v_mfma_f32_16x16x32_bf16 v[66:69], v[138:141], v[170:173], v[66:69]
	v_mfma_f32_16x16x32_bf16 v[62:65], v[142:145], v[166:169], v[62:65]
	v_mfma_f32_16x16x32_bf16 v[62:65], v[146:149], v[170:173], v[62:65]
	v_mfma_f32_16x16x32_bf16 v[50:53], v[134:137], v[174:177], v[50:53]
	v_mfma_f32_16x16x32_bf16 v[50:53], v[138:141], v[178:181], v[50:53]
	v_mfma_f32_16x16x32_bf16 v[46:49], v[142:145], v[174:177], v[46:49]
	v_mfma_f32_16x16x32_bf16 v[46:49], v[146:149], v[178:181], v[46:49]
	v_mfma_f32_16x16x32_bf16 v[30:33], v[134:137], v[182:185], v[30:33]
	v_mfma_f32_16x16x32_bf16 v[30:33], v[138:141], v[186:189], v[30:33]
	v_mfma_f32_16x16x32_bf16 v[26:29], v[142:145], v[182:185], v[26:29]
	v_mfma_f32_16x16x32_bf16 v[26:29], v[146:149], v[186:189], v[26:29]
	v_mfma_f32_16x16x32_bf16 v[14:17], v[134:137], v[190:193], v[14:17]
	v_mfma_f32_16x16x32_bf16 v[14:17], v[138:141], v[194:197], v[14:17]
	v_mfma_f32_16x16x32_bf16 v[10:13], v[142:145], v[190:193], v[10:13]
	v_mfma_f32_16x16x32_bf16 v[10:13], v[146:149], v[194:197], v[10:13]
	v_mfma_f32_16x16x32_bf16 v[58:61], v[150:153], v[166:169], v[58:61]
	v_mfma_f32_16x16x32_bf16 v[58:61], v[154:157], v[170:173], v[58:61]
	v_mfma_f32_16x16x32_bf16 v[54:57], v[158:161], v[166:169], v[54:57]
	v_mfma_f32_16x16x32_bf16 v[54:57], v[162:165], v[170:173], v[54:57]
	v_mfma_f32_16x16x32_bf16 v[40:43], v[150:153], v[174:177], v[42:45]
	v_mfma_f32_16x16x32_bf16 v[42:45], v[154:157], v[178:181], v[40:43]
	v_mfma_f32_16x16x32_bf16 v[36:39], v[158:161], v[174:177], v[36:39]
	v_mfma_f32_16x16x32_bf16 v[38:41], v[162:165], v[178:181], v[36:39]
	v_mfma_f32_16x16x32_bf16 v[22:25], v[150:153], v[182:185], v[22:25]
	v_mfma_f32_16x16x32_bf16 v[22:25], v[154:157], v[186:189], v[22:25]
	v_mfma_f32_16x16x32_bf16 v[18:21], v[158:161], v[182:185], v[18:21]
	v_mfma_f32_16x16x32_bf16 v[18:21], v[162:165], v[186:189], v[18:21]
	v_mfma_f32_16x16x32_bf16 v[6:9], v[150:153], v[190:193], v[6:9]
	v_mfma_f32_16x16x32_bf16 v[6:9], v[154:157], v[194:197], v[6:9]
	v_mfma_f32_16x16x32_bf16 v[2:5], v[158:161], v[190:193], v[2:5]
	v_mfma_f32_16x16x32_bf16 v[2:5], v[162:165], v[194:197], v[2:5]
	s_barrier
	s_setprio 0
	s_add_i32 vcc_lo, vcc_lo, 2
	s_add_u32 s36, s36, 0x100
	s_addc_u32 s37, s37, 0
	s_cmp_gt_u32 vcc_lo, 29
	s_cbranch_scc0 .LBB0_1644
	s_branch .LBB0_1648

.LBB0_1683:
	s_cmp_eq_u32 s76, 28
	s_cselect_b32 s79, s13, s41
	s_cselect_b32 s78, s25, s40
	s_cselect_b32 s37, s23, s75
	s_cselect_b32 s36, s52, s74
	s_setprio 1
	s_waitcnt lgkmcnt(0)
	v_mfma_f32_16x16x32_bf16 v[130:133], v[166:169], v[190:193], v[130:133]
	v_mfma_f32_16x16x32_bf16 v[126:129], v[174:177], v[190:193], v[126:129]
	v_mfma_f32_16x16x32_bf16 v[114:117], v[166:169], v[182:185], v[114:117]
	v_mfma_f32_16x16x32_bf16 v[110:113], v[174:177], v[182:185], v[110:113]
	v_mfma_f32_16x16x32_bf16 v[98:101], v[166:169], v[158:161], v[98:101]
	v_mfma_f32_16x16x32_bf16 v[94:97], v[174:177], v[158:161], v[94:97]
	v_mfma_f32_16x16x32_bf16 v[82:85], v[166:169], v[150:153], v[82:85]
	v_mfma_f32_16x16x32_bf16 v[78:81], v[174:177], v[150:153], v[78:81]
	v_mfma_f32_16x16x32_bf16 v[130:133], v[170:173], v[194:197], v[130:133]
	v_mfma_f32_16x16x32_bf16 v[126:129], v[178:181], v[194:197], v[126:129]
	v_mfma_f32_16x16x32_bf16 v[114:117], v[170:173], v[186:189], v[114:117]
	v_mfma_f32_16x16x32_bf16 v[110:113], v[178:181], v[186:189], v[110:113]
	v_mfma_f32_16x16x32_bf16 v[98:101], v[170:173], v[162:165], v[98:101]
	v_mfma_f32_16x16x32_bf16 v[94:97], v[178:181], v[162:165], v[94:97]
	v_mfma_f32_16x16x32_bf16 v[82:85], v[170:173], v[154:157], v[82:85]
	v_mfma_f32_16x16x32_bf16 v[78:81], v[178:181], v[154:157], v[78:81]
	v_mfma_f32_16x16x32_bf16 v[122:125], v[134:137], v[190:193], v[122:125]
	v_mfma_f32_16x16x32_bf16 v[118:121], v[142:145], v[190:193], v[118:121]
	v_mfma_f32_16x16x32_bf16 v[106:109], v[134:137], v[182:185], v[106:109]
	v_mfma_f32_16x16x32_bf16 v[102:105], v[142:145], v[182:185], v[102:105]
	v_mfma_f32_16x16x32_bf16 v[90:93], v[134:137], v[158:161], v[90:93]
	v_mfma_f32_16x16x32_bf16 v[86:89], v[142:145], v[158:161], v[86:89]
	v_mfma_f32_16x16x32_bf16 v[74:77], v[134:137], v[150:153], v[74:77]
	v_mfma_f32_16x16x32_bf16 v[70:73], v[142:145], v[150:153], v[70:73]
	v_mfma_f32_16x16x32_bf16 v[122:125], v[138:141], v[194:197], v[122:125]
	v_mfma_f32_16x16x32_bf16 v[118:121], v[146:149], v[194:197], v[118:121]
	v_mfma_f32_16x16x32_bf16 v[106:109], v[138:141], v[186:189], v[106:109]
	v_mfma_f32_16x16x32_bf16 v[102:105], v[146:149], v[186:189], v[102:105]
	v_mfma_f32_16x16x32_bf16 v[90:93], v[138:141], v[162:165], v[90:93]
	v_mfma_f32_16x16x32_bf16 v[86:89], v[146:149], v[162:165], v[86:89]
	v_mfma_f32_16x16x32_bf16 v[74:77], v[138:141], v[154:157], v[74:77]
	v_mfma_f32_16x16x32_bf16 v[70:73], v[146:149], v[154:157], v[70:73]
	s_setprio 0
	s_barrier
	s_mov_b32 m0, s54
	v_lshl_add_u64 v[36:37], s[36:37], 0, v[210:211]
	s_add_u32 vcc_lo, s36, 0x80000
	global_load_lds_dwordx4 v[36:37], off
	v_lshl_add_u64 v[198:199], s[36:37], 0, v[214:215]
	s_mov_b32 m0, s55
	s_addc_u32 vcc_hi, s37, 0
	global_load_lds_dwordx4 v[198:199], off
	v_lshl_add_u64 v[134:135], vcc, 0, v[210:211]
	s_mov_b32 m0, s59
	v_lshl_add_u64 v[200:201], s[78:79], 0, v[208:209]
	global_load_lds_dwordx4 v[134:135], off
	v_lshl_add_u64 v[134:135], vcc, 0, v[214:215]
	s_mov_b32 m0, s60
	v_lshl_add_u64 v[222:223], s[78:79], 0, v[212:213]
	global_load_lds_dwordx4 v[134:135], off
	s_mov_b32 m0, s43
	s_nop 0
	global_load_lds_dwordx4 v[200:201], off
	s_mov_b32 m0, s61
	s_nop 0
	global_load_lds_dwordx4 v[222:223], off
	s_waitcnt vmcnt(6)
	s_barrier
	s_barrier
	s_add_i32 s77, 0, 0x18000
	v_add_u32_e32 v34, s77, v220
	s_add_i32 s78, 0, 0x1c000
	ds_read_b128 v[134:137], v34
	ds_read_b128 v[138:141], v34 offset:1024
	ds_read_b128 v[142:145], v34 offset:2048
	ds_read_b128 v[146:149], v34 offset:3072
	v_add_u32_e32 v34, s78, v220
	ds_read_b128 v[150:153], v34
	ds_read_b128 v[154:157], v34 offset:1024
	ds_read_b128 v[158:161], v34 offset:2048
	ds_read_b128 v[162:165], v34 offset:3072
	ds_read_b128 v[166:169], v207 offset:32768
	ds_read_b128 v[170:173], v207 offset:33792
	ds_read_b128 v[174:177], v207 offset:34816
	ds_read_b128 v[178:181], v207 offset:35840
	ds_read_b128 v[182:185], v207 offset:36864
	ds_read_b128 v[186:189], v207 offset:37888
	ds_read_b128 v[190:193], v207 offset:38912
	ds_read_b128 v[194:197], v207 offset:39936
	s_waitcnt lgkmcnt(0)
	s_barrier
	s_setprio 1
	s_waitcnt lgkmcnt(0)
	v_mfma_f32_16x16x32_bf16 v[130:133], v[134:137], v[166:169], v[130:133]
	v_mfma_f32_16x16x32_bf16 v[126:129], v[142:145], v[166:169], v[126:129]
	v_mfma_f32_16x16x32_bf16 v[114:117], v[134:137], v[174:177], v[114:117]
	v_mfma_f32_16x16x32_bf16 v[110:113], v[142:145], v[174:177], v[110:113]
	v_mfma_f32_16x16x32_bf16 v[98:101], v[134:137], v[182:185], v[98:101]
	v_mfma_f32_16x16x32_bf16 v[94:97], v[142:145], v[182:185], v[94:97]
	v_mfma_f32_16x16x32_bf16 v[82:85], v[134:137], v[190:193], v[82:85]
	v_mfma_f32_16x16x32_bf16 v[78:81], v[142:145], v[190:193], v[78:81]
	v_mfma_f32_16x16x32_bf16 v[130:133], v[138:141], v[170:173], v[130:133]
	v_mfma_f32_16x16x32_bf16 v[126:129], v[146:149], v[170:173], v[126:129]
	v_mfma_f32_16x16x32_bf16 v[114:117], v[138:141], v[178:181], v[114:117]
	v_mfma_f32_16x16x32_bf16 v[110:113], v[146:149], v[178:181], v[110:113]
	v_mfma_f32_16x16x32_bf16 v[98:101], v[138:141], v[186:189], v[98:101]
	v_mfma_f32_16x16x32_bf16 v[94:97], v[146:149], v[186:189], v[94:97]
	v_mfma_f32_16x16x32_bf16 v[82:85], v[138:141], v[194:197], v[82:85]
	v_mfma_f32_16x16x32_bf16 v[78:81], v[146:149], v[194:197], v[78:81]
	v_mfma_f32_16x16x32_bf16 v[122:125], v[150:153], v[166:169], v[122:125]
	v_mfma_f32_16x16x32_bf16 v[118:121], v[158:161], v[166:169], v[118:121]
	v_mfma_f32_16x16x32_bf16 v[106:109], v[150:153], v[174:177], v[106:109]
	v_mfma_f32_16x16x32_bf16 v[102:105], v[158:161], v[174:177], v[102:105]
	v_mfma_f32_16x16x32_bf16 v[90:93], v[150:153], v[182:185], v[90:93]
	v_mfma_f32_16x16x32_bf16 v[86:89], v[158:161], v[182:185], v[86:89]
	v_mfma_f32_16x16x32_bf16 v[74:77], v[150:153], v[190:193], v[74:77]
	v_mfma_f32_16x16x32_bf16 v[70:73], v[158:161], v[190:193], v[70:73]
	v_mfma_f32_16x16x32_bf16 v[122:125], v[154:157], v[170:173], v[122:125]
	v_mfma_f32_16x16x32_bf16 v[118:121], v[162:165], v[170:173], v[118:121]
	v_mfma_f32_16x16x32_bf16 v[106:109], v[154:157], v[178:181], v[106:109]
	v_mfma_f32_16x16x32_bf16 v[102:105], v[162:165], v[178:181], v[102:105]
	v_mfma_f32_16x16x32_bf16 v[90:93], v[154:157], v[186:189], v[90:93]
	v_mfma_f32_16x16x32_bf16 v[86:89], v[162:165], v[186:189], v[86:89]
	v_mfma_f32_16x16x32_bf16 v[74:77], v[154:157], v[194:197], v[74:77]
	v_mfma_f32_16x16x32_bf16 v[70:73], v[162:165], v[194:197], v[70:73]
	s_setprio 0
	s_barrier
	s_add_i32 s77, s77, s42
	v_lshl_add_u64 v[36:37], v[36:37], 0, s[18:19]
	s_mov_b32 m0, s77
	s_nop 0
	global_load_lds_dwordx4 v[36:37], off
	s_add_i32 m0, s77, 0x2000
	s_add_u32 s36, s36, 0x80080
	v_lshl_add_u64 v[36:37], v[198:199], 0, s[18:19]
	s_addc_u32 s37, s37, 0
	s_add_i32 s77, s78, s42
	global_load_lds_dwordx4 v[36:37], off
	v_lshl_add_u64 v[36:37], s[36:37], 0, v[210:211]
	s_mov_b32 m0, s77
	s_nop 0
	global_load_lds_dwordx4 v[36:37], off
	v_lshl_add_u64 v[36:37], s[36:37], 0, v[214:215]
	s_add_i32 m0, s77, 0x2000
	s_nop 0
	global_load_lds_dwordx4 v[36:37], off
	v_lshl_add_u64 v[36:37], v[200:201], 0, s[18:19]
	s_mov_b32 m0, s62
	s_nop 0
	global_load_lds_dwordx4 v[36:37], off
	v_lshl_add_u64 v[36:37], v[222:223], 0, s[18:19]
	s_mov_b32 m0, s63
	s_nop 0
	global_load_lds_dwordx4 v[36:37], off
	s_waitcnt vmcnt(6)
	s_barrier
	s_barrier
	s_add_i32 s76, s76, 2
	s_add_u32 s40, s40, 0x100
	s_addc_u32 s41, s41, 0
	s_add_u32 s74, s74, 0x100
	s_addc_u32 s75, s75, 0
	s_cmp_gt_u32 s76, 29
	s_cbranch_scc1 .LBB0_1690
